# hand-scheduled P1 GEMM main loop (read-ahead frags, spread LDS stores), router matrix staged in LDS
# speedup vs baseline: 1.0942x; 1.0138x over previous
; DI int otid512() { int t = threadIdx.x; asm volatile("" : "+v"(t)); return t; }
; DI f16v mfma32(h8v a, h8v b, f16v c) { return __builtin_amdgcn_mfma_f32_32x32x16_f16(a, b, c, 0, 0, 0); }
; template <bool GATHER>
; DI void gemm256_main(const h16* __restrict__ A, int lda, const int* __restrict__ idx, int m0,
;                      const h16* __restrict__ B, int ldb, int n0, int K, h16* lds, f16v (&acc)[4][2]) {
;   const int tid = otid512(), lane = tid & 63, wv = tid >> 6, wm = wv >> 2, wn = wv & 3;
;   const int lr = tid >> 1, lc = (tid & 1) * 32;
;   unsigned ao = (unsigned)(GATHER ? idx[m0 + lr] : (m0 + lr)) * (unsigned)lda + lc;
;   unsigned bo = (unsigned)(n0 + lr) * (unsigned)ldb + lc;
;   const h16* ap = A; const h16* bp = B;
;     ...
;   u4v ra[4], rb[4];
;   const int nk = K >> 6;
;   __syncthreads();
; #pragma unroll
;   for (int i = 0; i < 4; ++i) { ra[i] = *(const u4v*)(AP_ + 8 * i); rb[i] = *(const u4v*)(BP_ + 8 * i); }
;   ao += 64; bo += 64;
; #pragma unroll
;   for (int i = 0; i < 4; ++i) { *(u4v*)&lds[lr * LDH + lc + 8 * i] = ra[i]; *(u4v*)&lds[(256 + lr) * LDH + lc + 8 * i] = rb[i]; }
; #pragma unroll
;   for (int i = 0; i < 4; ++i) { ra[i] = *(const u4v*)(AP_ + 8 * i); rb[i] = *(const u4v*)(BP_ + 8 * i); }
;   ao += 64; bo += 64;
;   __syncthreads();
;   for (int kt = 0; kt < nk; ++kt) {
;     const h16* As = lds + (kt & 1) * (512 * LDH);
;     const h16* Bs = As + 256 * LDH;
;     h16* Wn = lds + ((kt & 1) ^ 1) * (512 * LDH);
;     if (kt + 1 < nk) {
; #pragma unroll
;       for (int i = 0; i < 4; ++i) { *(u4v*)&Wn[lr * LDH + lc + 8 * i] = ra[i]; *(u4v*)&Wn[(256 + lr) * LDH + lc + 8 * i] = rb[i]; }
;     }
;     if (kt + 2 < nk) {
; #pragma unroll
;       for (int i = 0; i < 4; ++i) { ra[i] = *(const u4v*)(AP_ + 8 * i); rb[i] = *(const u4v*)(BP_ + 8 * i); }
;       ao += 64; bo += 64;
;     }
; #pragma unroll
;     for (int ks = 0; ks < 4; ++ks) {
;       h8v af[4], bf[2];
; #pragma unroll
;       for (int i = 0; i < 4; ++i) af[i] = *(const h8v*)&As[(wm * 128 + i * 32 + (lane & 31)) * LDH + ks * 16 + 8 * (lane >> 5)];
; #pragma unroll
;       for (int j = 0; j < 2; ++j) bf[j] = *(const h8v*)&Bs[(wn * 64 + j * 32 + (lane & 31)) * LDH + ks * 16 + 8 * (lane >> 5)];
; #pragma unroll
;       for (int i = 0; i < 4; ++i)
; #pragma unroll
;         for (int j = 0; j < 2; ++j) acc[i][j] = mfma32(bf[j], af[i], acc[i][j]);
;     }
;     __syncthreads();
.LBB0_101:
	s_mul_hi_i32 s2, s19, 0x66666667
	s_lshr_b32 s3, s2, 31
	s_ashr_i32 s2, s2, 3
	s_add_i32 s2, s2, s3
	v_mov_b32_e32 v1, v180
	s_mul_i32 s6, s2, 0x1400
	v_ashrrev_i32_e32 v66, 1, v1
	v_lshlrev_b32_e32 v2, 5, v1
	v_subrev_u32_e32 v3, s6, v66
	s_lshl_b32 s3, s2, 8
	v_and_b32_e32 v67, 32, v2
	v_add_u32_e32 v3, s18, v3
	v_add_u32_e32 v2, s3, v66
	v_lshl_or_b32 v133, v3, 10, v67
	v_readlane_b32 s8, v253, 0
	v_lshl_or_b32 v2, v2, 10, v67
	v_add_u32_e32 v18, 0x100000, v133
	v_mov_b32_e32 v3, v0
	v_mov_b32_e32 v19, v0
	v_readlane_b32 s9, v253, 1
	v_add_u32_e32 v34, 0x100040, v133
	v_mov_b32_e32 v35, v0
	v_lshl_add_u64 v[130:131], v[2:3], 1, s[40:41]
	v_lshl_add_u64 v[30:31], v[18:19], 1, s[8:9]
	v_lshl_add_u64 v[62:63], v[34:35], 1, s[8:9]
	s_barrier
	s_mulk_i32 s2, 0xec00
	s_add_i32 s2, s18, s2
	s_movk_i32 s4, 0x280
	s_cmpk_lt_u32 s2, 0x600
	v_mov_b32_e32 v248, v30
	v_mov_b32_e32 v249, v31
	v_lshrrev_b32_e32 v192, 1, v180
	v_and_b32_e32 v193, 1, v180
	v_mul_u32_u24_e32 v192, 0x90, v192
	v_lshl_add_u32 v178, v193, 6, v192
	v_add_u32_e32 v178, 16, v178
	v_add_u32_e32 v179, 0x12000, v178
	v_lshrrev_b32_e32 v192, 8, v180
	v_and_b32_e32 v194, 31, v180
	v_lshl_or_b32 v192, v192, 7, v194
	v_mul_u32_u24_e32 v192, 0x90, v192
	v_bfe_u32 v193, v180, 5, 1
	v_lshl_add_u32 v192, v193, 4, v192
	v_add_u32_e32 v215, 16, v192
	v_add_u32_e32 v212, 0x12000, v215
	v_bfe_u32 v192, v180, 6, 2
	v_lshl_or_b32 v192, v192, 6, v194
	v_mul_u32_u24_e32 v192, 0x90, v192
	v_lshl_add_u32 v192, v193, 4, v192
	v_add_u32_e32 v213, 0x9010, v192
	v_add_u32_e32 v214, 0x12000, v213
	global_load_dwordx4 v[134:137], v[130:131], off offset:0
	global_load_dwordx4 v[138:141], v[130:131], off offset:16
	global_load_dwordx4 v[142:145], v[130:131], off offset:32
	global_load_dwordx4 v[146:149], v[130:131], off offset:48
	global_load_dwordx4 v[150:153], v[248:249], off offset:0
	global_load_dwordx4 v[154:157], v[248:249], off offset:16
	global_load_dwordx4 v[158:161], v[248:249], off offset:32
	global_load_dwordx4 v[162:165], v[248:249], off offset:48
	s_waitcnt vmcnt(0)
	ds_write_b128 v178, v[134:137]
	ds_write_b128 v178, v[138:141] offset:16
	ds_write_b128 v178, v[142:145] offset:32
	ds_write_b128 v178, v[146:149] offset:48
	ds_write_b128 v178, v[150:153] offset:36864
	ds_write_b128 v178, v[154:157] offset:36880
	ds_write_b128 v178, v[158:161] offset:36896
	ds_write_b128 v178, v[162:165] offset:36912
	global_load_dwordx4 v[134:137], v[130:131], off offset:128
	global_load_dwordx4 v[138:141], v[130:131], off offset:144
	global_load_dwordx4 v[142:145], v[130:131], off offset:160
	global_load_dwordx4 v[146:149], v[130:131], off offset:176
	global_load_dwordx4 v[150:153], v[248:249], off offset:128
	global_load_dwordx4 v[154:157], v[248:249], off offset:144
	global_load_dwordx4 v[158:161], v[248:249], off offset:160
	global_load_dwordx4 v[162:165], v[248:249], off offset:176
	s_waitcnt lgkmcnt(0)
	s_barrier
	ds_read_b128 v[232:235], v213
	ds_read_b128 v[216:219], v215
	ds_read_b128 v[236:239], v213 offset:4608
	ds_read_b128 v[220:223], v215 offset:4608
	ds_read_b128 v[224:227], v215 offset:9216
	ds_read_b128 v[228:231], v215 offset:13824
	ds_read_b128 v[208:211], v213 offset:32
	ds_read_b128 v[240:243], v215 offset:32
	ds_read_b128 v[174:177], v213 offset:4640
	ds_read_b128 v[244:247], v215 offset:4640
	ds_read_b128 v[200:203], v215 offset:9248
	ds_read_b128 v[204:207], v215 offset:13856
	s_waitcnt vmcnt(4)
	ds_write_b128 v179, v[134:137]
	ds_write_b128 v179, v[138:141] offset:16
	ds_write_b128 v179, v[142:145] offset:32
	ds_write_b128 v179, v[146:149] offset:48
	global_load_dwordx4 v[134:137], v[130:131], off offset:256
	global_load_dwordx4 v[138:141], v[130:131], off offset:272
	global_load_dwordx4 v[142:145], v[130:131], off offset:288
	global_load_dwordx4 v[146:149], v[130:131], off offset:304
	s_waitcnt lgkmcnt(14)
	v_mfma_f32_32x32x16_f16 v[114:129], v[232:235], v[216:219], 0
	s_waitcnt lgkmcnt(13)
	v_mfma_f32_32x32x16_f16 v[98:113], v[236:239], v[216:219], 0
	s_waitcnt lgkmcnt(12)
	v_mfma_f32_32x32x16_f16 v[82:97], v[232:235], v[220:223], 0
	v_mfma_f32_32x32x16_f16 v[66:81], v[236:239], v[220:223], 0
	s_waitcnt lgkmcnt(11)
	v_mfma_f32_32x32x16_f16 v[50:65], v[232:235], v[224:227], 0
	v_mfma_f32_32x32x16_f16 v[34:49], v[236:239], v[224:227], 0
	s_waitcnt lgkmcnt(10)
	v_mfma_f32_32x32x16_f16 v[2:17], v[232:235], v[228:231], 0
	v_mfma_f32_32x32x16_f16 v[18:33], v[236:239], v[228:231], 0
	ds_read_b128 v[232:235], v213 offset:64
	ds_read_b128 v[216:219], v215 offset:64
	ds_read_b128 v[236:239], v213 offset:4672
	ds_read_b128 v[220:223], v215 offset:4672
	ds_read_b128 v[224:227], v215 offset:9280
	ds_read_b128 v[228:231], v215 offset:13888
	s_waitcnt vmcnt(4)
	ds_write_b128 v179, v[150:153] offset:36864
	ds_write_b128 v179, v[154:157] offset:36880
	ds_write_b128 v179, v[158:161] offset:36896
	ds_write_b128 v179, v[162:165] offset:36912
	global_load_dwordx4 v[150:153], v[248:249], off offset:256
	global_load_dwordx4 v[154:157], v[248:249], off offset:272
	global_load_dwordx4 v[158:161], v[248:249], off offset:288
	global_load_dwordx4 v[162:165], v[248:249], off offset:304
	s_waitcnt lgkmcnt(15)
	v_mfma_f32_32x32x16_f16 v[114:129], v[208:211], v[240:243], v[114:129]
	s_waitcnt lgkmcnt(15)
	v_mfma_f32_32x32x16_f16 v[98:113], v[174:177], v[240:243], v[98:113]
	s_waitcnt lgkmcnt(15)
	v_mfma_f32_32x32x16_f16 v[82:97], v[208:211], v[244:247], v[82:97]
	v_mfma_f32_32x32x16_f16 v[66:81], v[174:177], v[244:247], v[66:81]
	s_waitcnt lgkmcnt(15)
	v_mfma_f32_32x32x16_f16 v[50:65], v[208:211], v[200:203], v[50:65]
	v_mfma_f32_32x32x16_f16 v[34:49], v[174:177], v[200:203], v[34:49]
	s_waitcnt lgkmcnt(14)
	v_mfma_f32_32x32x16_f16 v[2:17], v[208:211], v[204:207], v[2:17]
	v_mfma_f32_32x32x16_f16 v[18:33], v[174:177], v[204:207], v[18:33]
	ds_read_b128 v[208:211], v213 offset:96
	ds_read_b128 v[240:243], v215 offset:96
	ds_read_b128 v[174:177], v213 offset:4704
	ds_read_b128 v[244:247], v215 offset:4704
	ds_read_b128 v[200:203], v215 offset:9312
	ds_read_b128 v[204:207], v215 offset:13920
	s_waitcnt lgkmcnt(14)
	v_mfma_f32_32x32x16_f16 v[114:129], v[232:235], v[216:219], v[114:129]
	s_waitcnt lgkmcnt(13)
	v_mfma_f32_32x32x16_f16 v[98:113], v[236:239], v[216:219], v[98:113]
	s_waitcnt lgkmcnt(12)
	v_mfma_f32_32x32x16_f16 v[82:97], v[232:235], v[220:223], v[82:97]
	v_mfma_f32_32x32x16_f16 v[66:81], v[236:239], v[220:223], v[66:81]
	s_waitcnt lgkmcnt(11)
	v_mfma_f32_32x32x16_f16 v[50:65], v[232:235], v[224:227], v[50:65]
	v_mfma_f32_32x32x16_f16 v[34:49], v[236:239], v[224:227], v[34:49]
	s_waitcnt lgkmcnt(10)
	v_mfma_f32_32x32x16_f16 v[2:17], v[232:235], v[228:231], v[2:17]
	v_mfma_f32_32x32x16_f16 v[18:33], v[236:239], v[228:231], v[18:33]
	s_waitcnt lgkmcnt(0)
	s_barrier
; DI f16v mfma32(h8v a, h8v b, f16v c) { return __builtin_amdgcn_mfma_f32_32x32x16_f16(a, b, c, 0, 0, 0); }
; template <bool GATHER>
; DI void gemm256_main(const h16* __restrict__ A, int lda, const int* __restrict__ idx, int m0,
;                      const h16* __restrict__ B, int ldb, int n0, int K, h16* lds, f16v (&acc)[4][2]) {
;     ...
;   for (int kt = 0; kt < nk; ++kt) {
;     const h16* As = lds + (kt & 1) * (512 * LDH);
;     const h16* Bs = As + 256 * LDH;
;     h16* Wn = lds + ((kt & 1) ^ 1) * (512 * LDH);
;     if (kt + 1 < nk) {
; #pragma unroll
;       for (int i = 0; i < 4; ++i) { *(u4v*)&Wn[lr * LDH + lc + 8 * i] = ra[i]; *(u4v*)&Wn[(256 + lr) * LDH + lc + 8 * i] = rb[i]; }
;     }
;     if (kt + 2 < nk) {
; #pragma unroll
;       for (int i = 0; i < 4; ++i) { ra[i] = *(const u4v*)(AP_ + 8 * i); rb[i] = *(const u4v*)(BP_ + 8 * i); }
;       ao += 64; bo += 64;
;     }
; #pragma unroll
;     for (int ks = 0; ks < 4; ++ks) {
;       h8v af[4], bf[2];
; #pragma unroll
;       for (int i = 0; i < 4; ++i) af[i] = *(const h8v*)&As[(wm * 128 + i * 32 + (lane & 31)) * LDH + ks * 16 + 8 * (lane >> 5)];
; #pragma unroll
;       for (int j = 0; j < 2; ++j) bf[j] = *(const h8v*)&Bs[(wn * 64 + j * 32 + (lane & 31)) * LDH + ks * 16 + 8 * (lane >> 5)];
; #pragma unroll
;       for (int i = 0; i < 4; ++i)
; #pragma unroll
;         for (int j = 0; j < 2; ++j) acc[i][j] = mfma32(bf[j], af[i], acc[i][j]);
;     }
;     __syncthreads();
	ds_read_b128 v[232:235], v214
	ds_read_b128 v[216:219], v212
	ds_read_b128 v[236:239], v214 offset:4608
	ds_read_b128 v[220:223], v212 offset:4608
	ds_read_b128 v[224:227], v212 offset:9216
	ds_read_b128 v[228:231], v212 offset:13824
	v_mfma_f32_32x32x16_f16 v[114:129], v[208:211], v[240:243], v[114:129]
	v_mfma_f32_32x32x16_f16 v[98:113], v[174:177], v[240:243], v[98:113]
	v_mfma_f32_32x32x16_f16 v[82:97], v[208:211], v[244:247], v[82:97]
	v_mfma_f32_32x32x16_f16 v[66:81], v[174:177], v[244:247], v[66:81]
	v_mfma_f32_32x32x16_f16 v[50:65], v[208:211], v[200:203], v[50:65]
	v_mfma_f32_32x32x16_f16 v[34:49], v[174:177], v[200:203], v[34:49]
	v_mfma_f32_32x32x16_f16 v[2:17], v[208:211], v[204:207], v[2:17]
	v_mfma_f32_32x32x16_f16 v[18:33], v[174:177], v[204:207], v[18:33]
	ds_read_b128 v[208:211], v214 offset:32
	ds_read_b128 v[240:243], v212 offset:32
	ds_read_b128 v[174:177], v214 offset:4640
	ds_read_b128 v[244:247], v212 offset:4640
	ds_read_b128 v[200:203], v212 offset:9248
	ds_read_b128 v[204:207], v212 offset:13856
	s_waitcnt vmcnt(4)
	ds_write_b128 v178, v[134:137]
	ds_write_b128 v178, v[138:141] offset:16
	ds_write_b128 v178, v[142:145] offset:32
	ds_write_b128 v178, v[146:149] offset:48
	global_load_dwordx4 v[134:137], v[130:131], off offset:384
	global_load_dwordx4 v[138:141], v[130:131], off offset:400
	global_load_dwordx4 v[142:145], v[130:131], off offset:416
	global_load_dwordx4 v[146:149], v[130:131], off offset:432
	s_waitcnt lgkmcnt(14)
	v_mfma_f32_32x32x16_f16 v[114:129], v[232:235], v[216:219], v[114:129]
	s_waitcnt lgkmcnt(13)
	v_mfma_f32_32x32x16_f16 v[98:113], v[236:239], v[216:219], v[98:113]
	s_waitcnt lgkmcnt(12)
	v_mfma_f32_32x32x16_f16 v[82:97], v[232:235], v[220:223], v[82:97]
	v_mfma_f32_32x32x16_f16 v[66:81], v[236:239], v[220:223], v[66:81]
	s_waitcnt lgkmcnt(11)
	v_mfma_f32_32x32x16_f16 v[50:65], v[232:235], v[224:227], v[50:65]
	v_mfma_f32_32x32x16_f16 v[34:49], v[236:239], v[224:227], v[34:49]
	s_waitcnt lgkmcnt(10)
	v_mfma_f32_32x32x16_f16 v[2:17], v[232:235], v[228:231], v[2:17]
	v_mfma_f32_32x32x16_f16 v[18:33], v[236:239], v[228:231], v[18:33]
	ds_read_b128 v[232:235], v214 offset:64
	ds_read_b128 v[216:219], v212 offset:64
	ds_read_b128 v[236:239], v214 offset:4672
	ds_read_b128 v[220:223], v212 offset:4672
	ds_read_b128 v[224:227], v212 offset:9280
	ds_read_b128 v[228:231], v212 offset:13888
	s_waitcnt vmcnt(4)
	ds_write_b128 v178, v[150:153] offset:36864
	ds_write_b128 v178, v[154:157] offset:36880
	ds_write_b128 v178, v[158:161] offset:36896
	ds_write_b128 v178, v[162:165] offset:36912
	global_load_dwordx4 v[150:153], v[248:249], off offset:384
	global_load_dwordx4 v[154:157], v[248:249], off offset:400
	global_load_dwordx4 v[158:161], v[248:249], off offset:416
	global_load_dwordx4 v[162:165], v[248:249], off offset:432
	s_waitcnt lgkmcnt(15)
	v_mfma_f32_32x32x16_f16 v[114:129], v[208:211], v[240:243], v[114:129]
	s_waitcnt lgkmcnt(15)
	v_mfma_f32_32x32x16_f16 v[98:113], v[174:177], v[240:243], v[98:113]
	s_waitcnt lgkmcnt(15)
	v_mfma_f32_32x32x16_f16 v[82:97], v[208:211], v[244:247], v[82:97]
	v_mfma_f32_32x32x16_f16 v[66:81], v[174:177], v[244:247], v[66:81]
	s_waitcnt lgkmcnt(15)
	v_mfma_f32_32x32x16_f16 v[50:65], v[208:211], v[200:203], v[50:65]
	v_mfma_f32_32x32x16_f16 v[34:49], v[174:177], v[200:203], v[34:49]
	s_waitcnt lgkmcnt(14)
	v_mfma_f32_32x32x16_f16 v[2:17], v[208:211], v[204:207], v[2:17]
	v_mfma_f32_32x32x16_f16 v[18:33], v[174:177], v[204:207], v[18:33]
	ds_read_b128 v[208:211], v214 offset:96
	ds_read_b128 v[240:243], v212 offset:96
	ds_read_b128 v[174:177], v214 offset:4704
	ds_read_b128 v[244:247], v212 offset:4704
	ds_read_b128 v[200:203], v212 offset:9312
	ds_read_b128 v[204:207], v212 offset:13920
	s_waitcnt lgkmcnt(14)
	v_mfma_f32_32x32x16_f16 v[114:129], v[232:235], v[216:219], v[114:129]
	s_waitcnt lgkmcnt(13)
	v_mfma_f32_32x32x16_f16 v[98:113], v[236:239], v[216:219], v[98:113]
	s_waitcnt lgkmcnt(12)
	v_mfma_f32_32x32x16_f16 v[82:97], v[232:235], v[220:223], v[82:97]
	v_mfma_f32_32x32x16_f16 v[66:81], v[236:239], v[220:223], v[66:81]
	s_waitcnt lgkmcnt(11)
	v_mfma_f32_32x32x16_f16 v[50:65], v[232:235], v[224:227], v[50:65]
	v_mfma_f32_32x32x16_f16 v[34:49], v[236:239], v[224:227], v[34:49]
	s_waitcnt lgkmcnt(10)
	v_mfma_f32_32x32x16_f16 v[2:17], v[232:235], v[228:231], v[2:17]
	v_mfma_f32_32x32x16_f16 v[18:33], v[236:239], v[228:231], v[18:33]
	s_waitcnt lgkmcnt(0)
	s_barrier
; DI f16v mfma32(h8v a, h8v b, f16v c) { return __builtin_amdgcn_mfma_f32_32x32x16_f16(a, b, c, 0, 0, 0); }
; template <bool GATHER>
; DI void gemm256_main(const h16* __restrict__ A, int lda, const int* __restrict__ idx, int m0,
;                      const h16* __restrict__ B, int ldb, int n0, int K, h16* lds, f16v (&acc)[4][2]) {
;     ...
;   for (int kt = 0; kt < nk; ++kt) {
;     const h16* As = lds + (kt & 1) * (512 * LDH);
;     const h16* Bs = As + 256 * LDH;
;     h16* Wn = lds + ((kt & 1) ^ 1) * (512 * LDH);
;     if (kt + 1 < nk) {
; #pragma unroll
;       for (int i = 0; i < 4; ++i) { *(u4v*)&Wn[lr * LDH + lc + 8 * i] = ra[i]; *(u4v*)&Wn[(256 + lr) * LDH + lc + 8 * i] = rb[i]; }
;     }
;     if (kt + 2 < nk) {
; #pragma unroll
;       for (int i = 0; i < 4; ++i) { ra[i] = *(const u4v*)(AP_ + 8 * i); rb[i] = *(const u4v*)(BP_ + 8 * i); }
;       ao += 64; bo += 64;
;     }
; #pragma unroll
;     for (int ks = 0; ks < 4; ++ks) {
;       h8v af[4], bf[2];
; #pragma unroll
;       for (int i = 0; i < 4; ++i) af[i] = *(const h8v*)&As[(wm * 128 + i * 32 + (lane & 31)) * LDH + ks * 16 + 8 * (lane >> 5)];
; #pragma unroll
;       for (int j = 0; j < 2; ++j) bf[j] = *(const h8v*)&Bs[(wn * 64 + j * 32 + (lane & 31)) * LDH + ks * 16 + 8 * (lane >> 5)];
; #pragma unroll
;       for (int i = 0; i < 4; ++i)
; #pragma unroll
;         for (int j = 0; j < 2; ++j) acc[i][j] = mfma32(bf[j], af[i], acc[i][j]);
;     }
;     __syncthreads();
	ds_read_b128 v[232:235], v213
	ds_read_b128 v[216:219], v215
	ds_read_b128 v[236:239], v213 offset:4608
	ds_read_b128 v[220:223], v215 offset:4608
	ds_read_b128 v[224:227], v215 offset:9216
	ds_read_b128 v[228:231], v215 offset:13824
	v_mfma_f32_32x32x16_f16 v[114:129], v[208:211], v[240:243], v[114:129]
	v_mfma_f32_32x32x16_f16 v[98:113], v[174:177], v[240:243], v[98:113]
	v_mfma_f32_32x32x16_f16 v[82:97], v[208:211], v[244:247], v[82:97]
	v_mfma_f32_32x32x16_f16 v[66:81], v[174:177], v[244:247], v[66:81]
	v_mfma_f32_32x32x16_f16 v[50:65], v[208:211], v[200:203], v[50:65]
	v_mfma_f32_32x32x16_f16 v[34:49], v[174:177], v[200:203], v[34:49]
	v_mfma_f32_32x32x16_f16 v[2:17], v[208:211], v[204:207], v[2:17]
	v_mfma_f32_32x32x16_f16 v[18:33], v[174:177], v[204:207], v[18:33]
	ds_read_b128 v[208:211], v213 offset:32
	ds_read_b128 v[240:243], v215 offset:32
	ds_read_b128 v[174:177], v213 offset:4640
	ds_read_b128 v[244:247], v215 offset:4640
	ds_read_b128 v[200:203], v215 offset:9248
	ds_read_b128 v[204:207], v215 offset:13856
	s_waitcnt vmcnt(4)
	ds_write_b128 v179, v[134:137]
	ds_write_b128 v179, v[138:141] offset:16
	ds_write_b128 v179, v[142:145] offset:32
	ds_write_b128 v179, v[146:149] offset:48
	global_load_dwordx4 v[134:137], v[130:131], off offset:512
	global_load_dwordx4 v[138:141], v[130:131], off offset:528
	global_load_dwordx4 v[142:145], v[130:131], off offset:544
	global_load_dwordx4 v[146:149], v[130:131], off offset:560
	s_waitcnt lgkmcnt(14)
	v_mfma_f32_32x32x16_f16 v[114:129], v[232:235], v[216:219], v[114:129]
	s_waitcnt lgkmcnt(13)
	v_mfma_f32_32x32x16_f16 v[98:113], v[236:239], v[216:219], v[98:113]
	s_waitcnt lgkmcnt(12)
	v_mfma_f32_32x32x16_f16 v[82:97], v[232:235], v[220:223], v[82:97]
	v_mfma_f32_32x32x16_f16 v[66:81], v[236:239], v[220:223], v[66:81]
	s_waitcnt lgkmcnt(11)
	v_mfma_f32_32x32x16_f16 v[50:65], v[232:235], v[224:227], v[50:65]
	v_mfma_f32_32x32x16_f16 v[34:49], v[236:239], v[224:227], v[34:49]
	s_waitcnt lgkmcnt(10)
	v_mfma_f32_32x32x16_f16 v[2:17], v[232:235], v[228:231], v[2:17]
	v_mfma_f32_32x32x16_f16 v[18:33], v[236:239], v[228:231], v[18:33]
	ds_read_b128 v[232:235], v213 offset:64
	ds_read_b128 v[216:219], v215 offset:64
	ds_read_b128 v[236:239], v213 offset:4672
	ds_read_b128 v[220:223], v215 offset:4672
	ds_read_b128 v[224:227], v215 offset:9280
	ds_read_b128 v[228:231], v215 offset:13888
	s_waitcnt vmcnt(4)
	ds_write_b128 v179, v[150:153] offset:36864
	ds_write_b128 v179, v[154:157] offset:36880
	ds_write_b128 v179, v[158:161] offset:36896
	ds_write_b128 v179, v[162:165] offset:36912
	global_load_dwordx4 v[150:153], v[248:249], off offset:512
	global_load_dwordx4 v[154:157], v[248:249], off offset:528
	global_load_dwordx4 v[158:161], v[248:249], off offset:544
	global_load_dwordx4 v[162:165], v[248:249], off offset:560
	s_waitcnt lgkmcnt(15)
	v_mfma_f32_32x32x16_f16 v[114:129], v[208:211], v[240:243], v[114:129]
	s_waitcnt lgkmcnt(15)
	v_mfma_f32_32x32x16_f16 v[98:113], v[174:177], v[240:243], v[98:113]
	s_waitcnt lgkmcnt(15)
	v_mfma_f32_32x32x16_f16 v[82:97], v[208:211], v[244:247], v[82:97]
	v_mfma_f32_32x32x16_f16 v[66:81], v[174:177], v[244:247], v[66:81]
	s_waitcnt lgkmcnt(15)
	v_mfma_f32_32x32x16_f16 v[50:65], v[208:211], v[200:203], v[50:65]
	v_mfma_f32_32x32x16_f16 v[34:49], v[174:177], v[200:203], v[34:49]
	s_waitcnt lgkmcnt(14)
	v_mfma_f32_32x32x16_f16 v[2:17], v[208:211], v[204:207], v[2:17]
	v_mfma_f32_32x32x16_f16 v[18:33], v[174:177], v[204:207], v[18:33]
	ds_read_b128 v[208:211], v213 offset:96
	ds_read_b128 v[240:243], v215 offset:96
	ds_read_b128 v[174:177], v213 offset:4704
	ds_read_b128 v[244:247], v215 offset:4704
	ds_read_b128 v[200:203], v215 offset:9312
	ds_read_b128 v[204:207], v215 offset:13920
	s_waitcnt lgkmcnt(14)
	v_mfma_f32_32x32x16_f16 v[114:129], v[232:235], v[216:219], v[114:129]
	s_waitcnt lgkmcnt(13)
	v_mfma_f32_32x32x16_f16 v[98:113], v[236:239], v[216:219], v[98:113]
	s_waitcnt lgkmcnt(12)
	v_mfma_f32_32x32x16_f16 v[82:97], v[232:235], v[220:223], v[82:97]
	v_mfma_f32_32x32x16_f16 v[66:81], v[236:239], v[220:223], v[66:81]
	s_waitcnt lgkmcnt(11)
	v_mfma_f32_32x32x16_f16 v[50:65], v[232:235], v[224:227], v[50:65]
	v_mfma_f32_32x32x16_f16 v[34:49], v[236:239], v[224:227], v[34:49]
	s_waitcnt lgkmcnt(10)
	v_mfma_f32_32x32x16_f16 v[2:17], v[232:235], v[228:231], v[2:17]
	v_mfma_f32_32x32x16_f16 v[18:33], v[236:239], v[228:231], v[18:33]
	s_waitcnt lgkmcnt(0)
	s_barrier
; DI f16v mfma32(h8v a, h8v b, f16v c) { return __builtin_amdgcn_mfma_f32_32x32x16_f16(a, b, c, 0, 0, 0); }
; template <bool GATHER>
; DI void gemm256_main(const h16* __restrict__ A, int lda, const int* __restrict__ idx, int m0,
;                      const h16* __restrict__ B, int ldb, int n0, int K, h16* lds, f16v (&acc)[4][2]) {
;     ...
;   for (int kt = 0; kt < nk; ++kt) {
;     const h16* As = lds + (kt & 1) * (512 * LDH);
;     const h16* Bs = As + 256 * LDH;
;     h16* Wn = lds + ((kt & 1) ^ 1) * (512 * LDH);
;     if (kt + 1 < nk) {
; #pragma unroll
;       for (int i = 0; i < 4; ++i) { *(u4v*)&Wn[lr * LDH + lc + 8 * i] = ra[i]; *(u4v*)&Wn[(256 + lr) * LDH + lc + 8 * i] = rb[i]; }
;     }
;     if (kt + 2 < nk) {
; #pragma unroll
;       for (int i = 0; i < 4; ++i) { ra[i] = *(const u4v*)(AP_ + 8 * i); rb[i] = *(const u4v*)(BP_ + 8 * i); }
;       ao += 64; bo += 64;
;     }
; #pragma unroll
;     for (int ks = 0; ks < 4; ++ks) {
;       h8v af[4], bf[2];
; #pragma unroll
;       for (int i = 0; i < 4; ++i) af[i] = *(const h8v*)&As[(wm * 128 + i * 32 + (lane & 31)) * LDH + ks * 16 + 8 * (lane >> 5)];
; #pragma unroll
;       for (int j = 0; j < 2; ++j) bf[j] = *(const h8v*)&Bs[(wn * 64 + j * 32 + (lane & 31)) * LDH + ks * 16 + 8 * (lane >> 5)];
; #pragma unroll
;       for (int i = 0; i < 4; ++i)
; #pragma unroll
;         for (int j = 0; j < 2; ++j) acc[i][j] = mfma32(bf[j], af[i], acc[i][j]);
;     }
;     __syncthreads();
	ds_read_b128 v[232:235], v214
	ds_read_b128 v[216:219], v212
	ds_read_b128 v[236:239], v214 offset:4608
	ds_read_b128 v[220:223], v212 offset:4608
	ds_read_b128 v[224:227], v212 offset:9216
	ds_read_b128 v[228:231], v212 offset:13824
	v_mfma_f32_32x32x16_f16 v[114:129], v[208:211], v[240:243], v[114:129]
	v_mfma_f32_32x32x16_f16 v[98:113], v[174:177], v[240:243], v[98:113]
	v_mfma_f32_32x32x16_f16 v[82:97], v[208:211], v[244:247], v[82:97]
	v_mfma_f32_32x32x16_f16 v[66:81], v[174:177], v[244:247], v[66:81]
	v_mfma_f32_32x32x16_f16 v[50:65], v[208:211], v[200:203], v[50:65]
	v_mfma_f32_32x32x16_f16 v[34:49], v[174:177], v[200:203], v[34:49]
	v_mfma_f32_32x32x16_f16 v[2:17], v[208:211], v[204:207], v[2:17]
	v_mfma_f32_32x32x16_f16 v[18:33], v[174:177], v[204:207], v[18:33]
	ds_read_b128 v[208:211], v214 offset:32
	ds_read_b128 v[240:243], v212 offset:32
	ds_read_b128 v[174:177], v214 offset:4640
	ds_read_b128 v[244:247], v212 offset:4640
	ds_read_b128 v[200:203], v212 offset:9248
	ds_read_b128 v[204:207], v212 offset:13856
	s_waitcnt vmcnt(4)
	ds_write_b128 v178, v[134:137]
	ds_write_b128 v178, v[138:141] offset:16
	ds_write_b128 v178, v[142:145] offset:32
	ds_write_b128 v178, v[146:149] offset:48
	global_load_dwordx4 v[134:137], v[130:131], off offset:640
	global_load_dwordx4 v[138:141], v[130:131], off offset:656
	global_load_dwordx4 v[142:145], v[130:131], off offset:672
	global_load_dwordx4 v[146:149], v[130:131], off offset:688
	s_waitcnt lgkmcnt(14)
	v_mfma_f32_32x32x16_f16 v[114:129], v[232:235], v[216:219], v[114:129]
	s_waitcnt lgkmcnt(13)
	v_mfma_f32_32x32x16_f16 v[98:113], v[236:239], v[216:219], v[98:113]
	s_waitcnt lgkmcnt(12)
	v_mfma_f32_32x32x16_f16 v[82:97], v[232:235], v[220:223], v[82:97]
	v_mfma_f32_32x32x16_f16 v[66:81], v[236:239], v[220:223], v[66:81]
	s_waitcnt lgkmcnt(11)
	v_mfma_f32_32x32x16_f16 v[50:65], v[232:235], v[224:227], v[50:65]
	v_mfma_f32_32x32x16_f16 v[34:49], v[236:239], v[224:227], v[34:49]
	s_waitcnt lgkmcnt(10)
	v_mfma_f32_32x32x16_f16 v[2:17], v[232:235], v[228:231], v[2:17]
	v_mfma_f32_32x32x16_f16 v[18:33], v[236:239], v[228:231], v[18:33]
	ds_read_b128 v[232:235], v214 offset:64
	ds_read_b128 v[216:219], v212 offset:64
	ds_read_b128 v[236:239], v214 offset:4672
	ds_read_b128 v[220:223], v212 offset:4672
	ds_read_b128 v[224:227], v212 offset:9280
	ds_read_b128 v[228:231], v212 offset:13888
	s_waitcnt vmcnt(4)
	ds_write_b128 v178, v[150:153] offset:36864
	ds_write_b128 v178, v[154:157] offset:36880
	ds_write_b128 v178, v[158:161] offset:36896
	ds_write_b128 v178, v[162:165] offset:36912
	global_load_dwordx4 v[150:153], v[248:249], off offset:640
	global_load_dwordx4 v[154:157], v[248:249], off offset:656
	global_load_dwordx4 v[158:161], v[248:249], off offset:672
	global_load_dwordx4 v[162:165], v[248:249], off offset:688
	s_waitcnt lgkmcnt(15)
	v_mfma_f32_32x32x16_f16 v[114:129], v[208:211], v[240:243], v[114:129]
	s_waitcnt lgkmcnt(15)
	v_mfma_f32_32x32x16_f16 v[98:113], v[174:177], v[240:243], v[98:113]
	s_waitcnt lgkmcnt(15)
	v_mfma_f32_32x32x16_f16 v[82:97], v[208:211], v[244:247], v[82:97]
	v_mfma_f32_32x32x16_f16 v[66:81], v[174:177], v[244:247], v[66:81]
	s_waitcnt lgkmcnt(15)
	v_mfma_f32_32x32x16_f16 v[50:65], v[208:211], v[200:203], v[50:65]
	v_mfma_f32_32x32x16_f16 v[34:49], v[174:177], v[200:203], v[34:49]
	s_waitcnt lgkmcnt(14)
	v_mfma_f32_32x32x16_f16 v[2:17], v[208:211], v[204:207], v[2:17]
	v_mfma_f32_32x32x16_f16 v[18:33], v[174:177], v[204:207], v[18:33]
	ds_read_b128 v[208:211], v214 offset:96
	ds_read_b128 v[240:243], v212 offset:96
	ds_read_b128 v[174:177], v214 offset:4704
	ds_read_b128 v[244:247], v212 offset:4704
	ds_read_b128 v[200:203], v212 offset:9312
	ds_read_b128 v[204:207], v212 offset:13920
	s_waitcnt lgkmcnt(14)
	v_mfma_f32_32x32x16_f16 v[114:129], v[232:235], v[216:219], v[114:129]
	s_waitcnt lgkmcnt(13)
	v_mfma_f32_32x32x16_f16 v[98:113], v[236:239], v[216:219], v[98:113]
	s_waitcnt lgkmcnt(12)
	v_mfma_f32_32x32x16_f16 v[82:97], v[232:235], v[220:223], v[82:97]
	v_mfma_f32_32x32x16_f16 v[66:81], v[236:239], v[220:223], v[66:81]
	s_waitcnt lgkmcnt(11)
	v_mfma_f32_32x32x16_f16 v[50:65], v[232:235], v[224:227], v[50:65]
	v_mfma_f32_32x32x16_f16 v[34:49], v[236:239], v[224:227], v[34:49]
	s_waitcnt lgkmcnt(10)
	v_mfma_f32_32x32x16_f16 v[2:17], v[232:235], v[228:231], v[2:17]
	v_mfma_f32_32x32x16_f16 v[18:33], v[236:239], v[228:231], v[18:33]
	s_waitcnt lgkmcnt(0)
	s_barrier
; DI f16v mfma32(h8v a, h8v b, f16v c) { return __builtin_amdgcn_mfma_f32_32x32x16_f16(a, b, c, 0, 0, 0); }
; template <bool GATHER>
; DI void gemm256_main(const h16* __restrict__ A, int lda, const int* __restrict__ idx, int m0,
;                      const h16* __restrict__ B, int ldb, int n0, int K, h16* lds, f16v (&acc)[4][2]) {
;     ...
;   for (int kt = 0; kt < nk; ++kt) {
;     const h16* As = lds + (kt & 1) * (512 * LDH);
;     const h16* Bs = As + 256 * LDH;
;     h16* Wn = lds + ((kt & 1) ^ 1) * (512 * LDH);
;     if (kt + 1 < nk) {
; #pragma unroll
;       for (int i = 0; i < 4; ++i) { *(u4v*)&Wn[lr * LDH + lc + 8 * i] = ra[i]; *(u4v*)&Wn[(256 + lr) * LDH + lc + 8 * i] = rb[i]; }
;     }
;     if (kt + 2 < nk) {
; #pragma unroll
;       for (int i = 0; i < 4; ++i) { ra[i] = *(const u4v*)(AP_ + 8 * i); rb[i] = *(const u4v*)(BP_ + 8 * i); }
;       ao += 64; bo += 64;
;     }
; #pragma unroll
;     for (int ks = 0; ks < 4; ++ks) {
;       h8v af[4], bf[2];
; #pragma unroll
;       for (int i = 0; i < 4; ++i) af[i] = *(const h8v*)&As[(wm * 128 + i * 32 + (lane & 31)) * LDH + ks * 16 + 8 * (lane >> 5)];
; #pragma unroll
;       for (int j = 0; j < 2; ++j) bf[j] = *(const h8v*)&Bs[(wn * 64 + j * 32 + (lane & 31)) * LDH + ks * 16 + 8 * (lane >> 5)];
; #pragma unroll
;       for (int i = 0; i < 4; ++i)
; #pragma unroll
;         for (int j = 0; j < 2; ++j) acc[i][j] = mfma32(bf[j], af[i], acc[i][j]);
;     }
;     __syncthreads();
	ds_read_b128 v[232:235], v213
	ds_read_b128 v[216:219], v215
	ds_read_b128 v[236:239], v213 offset:4608
	ds_read_b128 v[220:223], v215 offset:4608
	ds_read_b128 v[224:227], v215 offset:9216
	ds_read_b128 v[228:231], v215 offset:13824
	v_mfma_f32_32x32x16_f16 v[114:129], v[208:211], v[240:243], v[114:129]
	v_mfma_f32_32x32x16_f16 v[98:113], v[174:177], v[240:243], v[98:113]
	v_mfma_f32_32x32x16_f16 v[82:97], v[208:211], v[244:247], v[82:97]
	v_mfma_f32_32x32x16_f16 v[66:81], v[174:177], v[244:247], v[66:81]
	v_mfma_f32_32x32x16_f16 v[50:65], v[208:211], v[200:203], v[50:65]
	v_mfma_f32_32x32x16_f16 v[34:49], v[174:177], v[200:203], v[34:49]
	v_mfma_f32_32x32x16_f16 v[2:17], v[208:211], v[204:207], v[2:17]
	v_mfma_f32_32x32x16_f16 v[18:33], v[174:177], v[204:207], v[18:33]
	ds_read_b128 v[208:211], v213 offset:32
	ds_read_b128 v[240:243], v215 offset:32
	ds_read_b128 v[174:177], v213 offset:4640
	ds_read_b128 v[244:247], v215 offset:4640
	ds_read_b128 v[200:203], v215 offset:9248
	ds_read_b128 v[204:207], v215 offset:13856
	s_waitcnt vmcnt(4)
	ds_write_b128 v179, v[134:137]
	ds_write_b128 v179, v[138:141] offset:16
	ds_write_b128 v179, v[142:145] offset:32
	ds_write_b128 v179, v[146:149] offset:48
	global_load_dwordx4 v[134:137], v[130:131], off offset:768
	global_load_dwordx4 v[138:141], v[130:131], off offset:784
	global_load_dwordx4 v[142:145], v[130:131], off offset:800
	global_load_dwordx4 v[146:149], v[130:131], off offset:816
	s_waitcnt lgkmcnt(14)
	v_mfma_f32_32x32x16_f16 v[114:129], v[232:235], v[216:219], v[114:129]
	s_waitcnt lgkmcnt(13)
	v_mfma_f32_32x32x16_f16 v[98:113], v[236:239], v[216:219], v[98:113]
	s_waitcnt lgkmcnt(12)
	v_mfma_f32_32x32x16_f16 v[82:97], v[232:235], v[220:223], v[82:97]
	v_mfma_f32_32x32x16_f16 v[66:81], v[236:239], v[220:223], v[66:81]
	s_waitcnt lgkmcnt(11)
	v_mfma_f32_32x32x16_f16 v[50:65], v[232:235], v[224:227], v[50:65]
	v_mfma_f32_32x32x16_f16 v[34:49], v[236:239], v[224:227], v[34:49]
	s_waitcnt lgkmcnt(10)
	v_mfma_f32_32x32x16_f16 v[2:17], v[232:235], v[228:231], v[2:17]
	v_mfma_f32_32x32x16_f16 v[18:33], v[236:239], v[228:231], v[18:33]
	ds_read_b128 v[232:235], v213 offset:64
	ds_read_b128 v[216:219], v215 offset:64
	ds_read_b128 v[236:239], v213 offset:4672
	ds_read_b128 v[220:223], v215 offset:4672
	ds_read_b128 v[224:227], v215 offset:9280
	ds_read_b128 v[228:231], v215 offset:13888
	s_waitcnt vmcnt(4)
	ds_write_b128 v179, v[150:153] offset:36864
	ds_write_b128 v179, v[154:157] offset:36880
	ds_write_b128 v179, v[158:161] offset:36896
	ds_write_b128 v179, v[162:165] offset:36912
	global_load_dwordx4 v[150:153], v[248:249], off offset:768
	global_load_dwordx4 v[154:157], v[248:249], off offset:784
	global_load_dwordx4 v[158:161], v[248:249], off offset:800
	global_load_dwordx4 v[162:165], v[248:249], off offset:816
	s_waitcnt lgkmcnt(15)
	v_mfma_f32_32x32x16_f16 v[114:129], v[208:211], v[240:243], v[114:129]
	s_waitcnt lgkmcnt(15)
	v_mfma_f32_32x32x16_f16 v[98:113], v[174:177], v[240:243], v[98:113]
	s_waitcnt lgkmcnt(15)
	v_mfma_f32_32x32x16_f16 v[82:97], v[208:211], v[244:247], v[82:97]
	v_mfma_f32_32x32x16_f16 v[66:81], v[174:177], v[244:247], v[66:81]
	s_waitcnt lgkmcnt(15)
	v_mfma_f32_32x32x16_f16 v[50:65], v[208:211], v[200:203], v[50:65]
	v_mfma_f32_32x32x16_f16 v[34:49], v[174:177], v[200:203], v[34:49]
	s_waitcnt lgkmcnt(14)
	v_mfma_f32_32x32x16_f16 v[2:17], v[208:211], v[204:207], v[2:17]
	v_mfma_f32_32x32x16_f16 v[18:33], v[174:177], v[204:207], v[18:33]
	ds_read_b128 v[208:211], v213 offset:96
	ds_read_b128 v[240:243], v215 offset:96
	ds_read_b128 v[174:177], v213 offset:4704
	ds_read_b128 v[244:247], v215 offset:4704
	ds_read_b128 v[200:203], v215 offset:9312
	ds_read_b128 v[204:207], v215 offset:13920
	s_waitcnt lgkmcnt(14)
	v_mfma_f32_32x32x16_f16 v[114:129], v[232:235], v[216:219], v[114:129]
	s_waitcnt lgkmcnt(13)
	v_mfma_f32_32x32x16_f16 v[98:113], v[236:239], v[216:219], v[98:113]
	s_waitcnt lgkmcnt(12)
	v_mfma_f32_32x32x16_f16 v[82:97], v[232:235], v[220:223], v[82:97]
	v_mfma_f32_32x32x16_f16 v[66:81], v[236:239], v[220:223], v[66:81]
	s_waitcnt lgkmcnt(11)
	v_mfma_f32_32x32x16_f16 v[50:65], v[232:235], v[224:227], v[50:65]
	v_mfma_f32_32x32x16_f16 v[34:49], v[236:239], v[224:227], v[34:49]
	s_waitcnt lgkmcnt(10)
	v_mfma_f32_32x32x16_f16 v[2:17], v[232:235], v[228:231], v[2:17]
	v_mfma_f32_32x32x16_f16 v[18:33], v[236:239], v[228:231], v[18:33]
	s_waitcnt lgkmcnt(0)
	s_barrier
; DI f16v mfma32(h8v a, h8v b, f16v c) { return __builtin_amdgcn_mfma_f32_32x32x16_f16(a, b, c, 0, 0, 0); }
; template <bool GATHER>
; DI void gemm256_main(const h16* __restrict__ A, int lda, const int* __restrict__ idx, int m0,
;                      const h16* __restrict__ B, int ldb, int n0, int K, h16* lds, f16v (&acc)[4][2]) {
;     ...
;   for (int kt = 0; kt < nk; ++kt) {
;     const h16* As = lds + (kt & 1) * (512 * LDH);
;     const h16* Bs = As + 256 * LDH;
;     h16* Wn = lds + ((kt & 1) ^ 1) * (512 * LDH);
;     if (kt + 1 < nk) {
; #pragma unroll
;       for (int i = 0; i < 4; ++i) { *(u4v*)&Wn[lr * LDH + lc + 8 * i] = ra[i]; *(u4v*)&Wn[(256 + lr) * LDH + lc + 8 * i] = rb[i]; }
;     }
;     if (kt + 2 < nk) {
; #pragma unroll
;       for (int i = 0; i < 4; ++i) { ra[i] = *(const u4v*)(AP_ + 8 * i); rb[i] = *(const u4v*)(BP_ + 8 * i); }
;       ao += 64; bo += 64;
;     }
; #pragma unroll
;     for (int ks = 0; ks < 4; ++ks) {
;       h8v af[4], bf[2];
; #pragma unroll
;       for (int i = 0; i < 4; ++i) af[i] = *(const h8v*)&As[(wm * 128 + i * 32 + (lane & 31)) * LDH + ks * 16 + 8 * (lane >> 5)];
; #pragma unroll
;       for (int j = 0; j < 2; ++j) bf[j] = *(const h8v*)&Bs[(wn * 64 + j * 32 + (lane & 31)) * LDH + ks * 16 + 8 * (lane >> 5)];
; #pragma unroll
;       for (int i = 0; i < 4; ++i)
; #pragma unroll
;         for (int j = 0; j < 2; ++j) acc[i][j] = mfma32(bf[j], af[i], acc[i][j]);
;     }
;     __syncthreads();
	ds_read_b128 v[232:235], v214
	ds_read_b128 v[216:219], v212
	ds_read_b128 v[236:239], v214 offset:4608
	ds_read_b128 v[220:223], v212 offset:4608
	ds_read_b128 v[224:227], v212 offset:9216
	ds_read_b128 v[228:231], v212 offset:13824
	v_mfma_f32_32x32x16_f16 v[114:129], v[208:211], v[240:243], v[114:129]
	v_mfma_f32_32x32x16_f16 v[98:113], v[174:177], v[240:243], v[98:113]
	v_mfma_f32_32x32x16_f16 v[82:97], v[208:211], v[244:247], v[82:97]
	v_mfma_f32_32x32x16_f16 v[66:81], v[174:177], v[244:247], v[66:81]
	v_mfma_f32_32x32x16_f16 v[50:65], v[208:211], v[200:203], v[50:65]
	v_mfma_f32_32x32x16_f16 v[34:49], v[174:177], v[200:203], v[34:49]
	v_mfma_f32_32x32x16_f16 v[2:17], v[208:211], v[204:207], v[2:17]
	v_mfma_f32_32x32x16_f16 v[18:33], v[174:177], v[204:207], v[18:33]
	ds_read_b128 v[208:211], v214 offset:32
	ds_read_b128 v[240:243], v212 offset:32
	ds_read_b128 v[174:177], v214 offset:4640
	ds_read_b128 v[244:247], v212 offset:4640
	ds_read_b128 v[200:203], v212 offset:9248
	ds_read_b128 v[204:207], v212 offset:13856
	s_waitcnt vmcnt(4)
	ds_write_b128 v178, v[134:137]
	ds_write_b128 v178, v[138:141] offset:16
	ds_write_b128 v178, v[142:145] offset:32
	ds_write_b128 v178, v[146:149] offset:48
	global_load_dwordx4 v[134:137], v[130:131], off offset:896
	global_load_dwordx4 v[138:141], v[130:131], off offset:912
	global_load_dwordx4 v[142:145], v[130:131], off offset:928
	global_load_dwordx4 v[146:149], v[130:131], off offset:944
	s_waitcnt lgkmcnt(14)
	v_mfma_f32_32x32x16_f16 v[114:129], v[232:235], v[216:219], v[114:129]
	s_waitcnt lgkmcnt(13)
	v_mfma_f32_32x32x16_f16 v[98:113], v[236:239], v[216:219], v[98:113]
	s_waitcnt lgkmcnt(12)
	v_mfma_f32_32x32x16_f16 v[82:97], v[232:235], v[220:223], v[82:97]
	v_mfma_f32_32x32x16_f16 v[66:81], v[236:239], v[220:223], v[66:81]
	s_waitcnt lgkmcnt(11)
	v_mfma_f32_32x32x16_f16 v[50:65], v[232:235], v[224:227], v[50:65]
	v_mfma_f32_32x32x16_f16 v[34:49], v[236:239], v[224:227], v[34:49]
	s_waitcnt lgkmcnt(10)
	v_mfma_f32_32x32x16_f16 v[2:17], v[232:235], v[228:231], v[2:17]
	v_mfma_f32_32x32x16_f16 v[18:33], v[236:239], v[228:231], v[18:33]
	ds_read_b128 v[232:235], v214 offset:64
	ds_read_b128 v[216:219], v212 offset:64
	ds_read_b128 v[236:239], v214 offset:4672
	ds_read_b128 v[220:223], v212 offset:4672
	ds_read_b128 v[224:227], v212 offset:9280
	ds_read_b128 v[228:231], v212 offset:13888
	s_waitcnt vmcnt(4)
	ds_write_b128 v178, v[150:153] offset:36864
	ds_write_b128 v178, v[154:157] offset:36880
	ds_write_b128 v178, v[158:161] offset:36896
	ds_write_b128 v178, v[162:165] offset:36912
	global_load_dwordx4 v[150:153], v[248:249], off offset:896
	global_load_dwordx4 v[154:157], v[248:249], off offset:912
	global_load_dwordx4 v[158:161], v[248:249], off offset:928
	global_load_dwordx4 v[162:165], v[248:249], off offset:944
	s_waitcnt lgkmcnt(15)
	v_mfma_f32_32x32x16_f16 v[114:129], v[208:211], v[240:243], v[114:129]
	s_waitcnt lgkmcnt(15)
	v_mfma_f32_32x32x16_f16 v[98:113], v[174:177], v[240:243], v[98:113]
	s_waitcnt lgkmcnt(15)
	v_mfma_f32_32x32x16_f16 v[82:97], v[208:211], v[244:247], v[82:97]
	v_mfma_f32_32x32x16_f16 v[66:81], v[174:177], v[244:247], v[66:81]
	s_waitcnt lgkmcnt(15)
	v_mfma_f32_32x32x16_f16 v[50:65], v[208:211], v[200:203], v[50:65]
	v_mfma_f32_32x32x16_f16 v[34:49], v[174:177], v[200:203], v[34:49]
	s_waitcnt lgkmcnt(14)
	v_mfma_f32_32x32x16_f16 v[2:17], v[208:211], v[204:207], v[2:17]
	v_mfma_f32_32x32x16_f16 v[18:33], v[174:177], v[204:207], v[18:33]
	ds_read_b128 v[208:211], v214 offset:96
	ds_read_b128 v[240:243], v212 offset:96
	ds_read_b128 v[174:177], v214 offset:4704
	ds_read_b128 v[244:247], v212 offset:4704
	ds_read_b128 v[200:203], v212 offset:9312
	ds_read_b128 v[204:207], v212 offset:13920
	s_waitcnt lgkmcnt(14)
	v_mfma_f32_32x32x16_f16 v[114:129], v[232:235], v[216:219], v[114:129]
	s_waitcnt lgkmcnt(13)
	v_mfma_f32_32x32x16_f16 v[98:113], v[236:239], v[216:219], v[98:113]
	s_waitcnt lgkmcnt(12)
	v_mfma_f32_32x32x16_f16 v[82:97], v[232:235], v[220:223], v[82:97]
	v_mfma_f32_32x32x16_f16 v[66:81], v[236:239], v[220:223], v[66:81]
	s_waitcnt lgkmcnt(11)
	v_mfma_f32_32x32x16_f16 v[50:65], v[232:235], v[224:227], v[50:65]
	v_mfma_f32_32x32x16_f16 v[34:49], v[236:239], v[224:227], v[34:49]
	s_waitcnt lgkmcnt(10)
	v_mfma_f32_32x32x16_f16 v[2:17], v[232:235], v[228:231], v[2:17]
	v_mfma_f32_32x32x16_f16 v[18:33], v[236:239], v[228:231], v[18:33]
	s_waitcnt lgkmcnt(0)
	s_barrier
; DI f16v mfma32(h8v a, h8v b, f16v c) { return __builtin_amdgcn_mfma_f32_32x32x16_f16(a, b, c, 0, 0, 0); }
; template <bool GATHER>
; DI void gemm256_main(const h16* __restrict__ A, int lda, const int* __restrict__ idx, int m0,
;                      const h16* __restrict__ B, int ldb, int n0, int K, h16* lds, f16v (&acc)[4][2]) {
;     ...
;   for (int kt = 0; kt < nk; ++kt) {
;     const h16* As = lds + (kt & 1) * (512 * LDH);
;     const h16* Bs = As + 256 * LDH;
;     h16* Wn = lds + ((kt & 1) ^ 1) * (512 * LDH);
;     if (kt + 1 < nk) {
; #pragma unroll
;       for (int i = 0; i < 4; ++i) { *(u4v*)&Wn[lr * LDH + lc + 8 * i] = ra[i]; *(u4v*)&Wn[(256 + lr) * LDH + lc + 8 * i] = rb[i]; }
;     }
;     if (kt + 2 < nk) {
; #pragma unroll
;       for (int i = 0; i < 4; ++i) { ra[i] = *(const u4v*)(AP_ + 8 * i); rb[i] = *(const u4v*)(BP_ + 8 * i); }
;       ao += 64; bo += 64;
;     }
; #pragma unroll
;     for (int ks = 0; ks < 4; ++ks) {
;       h8v af[4], bf[2];
; #pragma unroll
;       for (int i = 0; i < 4; ++i) af[i] = *(const h8v*)&As[(wm * 128 + i * 32 + (lane & 31)) * LDH + ks * 16 + 8 * (lane >> 5)];
; #pragma unroll
;       for (int j = 0; j < 2; ++j) bf[j] = *(const h8v*)&Bs[(wn * 64 + j * 32 + (lane & 31)) * LDH + ks * 16 + 8 * (lane >> 5)];
; #pragma unroll
;       for (int i = 0; i < 4; ++i)
; #pragma unroll
;         for (int j = 0; j < 2; ++j) acc[i][j] = mfma32(bf[j], af[i], acc[i][j]);
;     }
;     __syncthreads();
	ds_read_b128 v[232:235], v213
	ds_read_b128 v[216:219], v215
	ds_read_b128 v[236:239], v213 offset:4608
	ds_read_b128 v[220:223], v215 offset:4608
	ds_read_b128 v[224:227], v215 offset:9216
	ds_read_b128 v[228:231], v215 offset:13824
	v_mfma_f32_32x32x16_f16 v[114:129], v[208:211], v[240:243], v[114:129]
	v_mfma_f32_32x32x16_f16 v[98:113], v[174:177], v[240:243], v[98:113]
	v_mfma_f32_32x32x16_f16 v[82:97], v[208:211], v[244:247], v[82:97]
	v_mfma_f32_32x32x16_f16 v[66:81], v[174:177], v[244:247], v[66:81]
	v_mfma_f32_32x32x16_f16 v[50:65], v[208:211], v[200:203], v[50:65]
	v_mfma_f32_32x32x16_f16 v[34:49], v[174:177], v[200:203], v[34:49]
	v_mfma_f32_32x32x16_f16 v[2:17], v[208:211], v[204:207], v[2:17]
	v_mfma_f32_32x32x16_f16 v[18:33], v[174:177], v[204:207], v[18:33]
	ds_read_b128 v[208:211], v213 offset:32
	ds_read_b128 v[240:243], v215 offset:32
	ds_read_b128 v[174:177], v213 offset:4640
	ds_read_b128 v[244:247], v215 offset:4640
	ds_read_b128 v[200:203], v215 offset:9248
	ds_read_b128 v[204:207], v215 offset:13856
	s_waitcnt vmcnt(4)
	ds_write_b128 v179, v[134:137]
	ds_write_b128 v179, v[138:141] offset:16
	ds_write_b128 v179, v[142:145] offset:32
	ds_write_b128 v179, v[146:149] offset:48
	global_load_dwordx4 v[134:137], v[130:131], off offset:1024
	global_load_dwordx4 v[138:141], v[130:131], off offset:1040
	global_load_dwordx4 v[142:145], v[130:131], off offset:1056
	global_load_dwordx4 v[146:149], v[130:131], off offset:1072
	s_waitcnt lgkmcnt(14)
	v_mfma_f32_32x32x16_f16 v[114:129], v[232:235], v[216:219], v[114:129]
	s_waitcnt lgkmcnt(13)
	v_mfma_f32_32x32x16_f16 v[98:113], v[236:239], v[216:219], v[98:113]
	s_waitcnt lgkmcnt(12)
	v_mfma_f32_32x32x16_f16 v[82:97], v[232:235], v[220:223], v[82:97]
	v_mfma_f32_32x32x16_f16 v[66:81], v[236:239], v[220:223], v[66:81]
	s_waitcnt lgkmcnt(11)
	v_mfma_f32_32x32x16_f16 v[50:65], v[232:235], v[224:227], v[50:65]
	v_mfma_f32_32x32x16_f16 v[34:49], v[236:239], v[224:227], v[34:49]
	s_waitcnt lgkmcnt(10)
	v_mfma_f32_32x32x16_f16 v[2:17], v[232:235], v[228:231], v[2:17]
	v_mfma_f32_32x32x16_f16 v[18:33], v[236:239], v[228:231], v[18:33]
	ds_read_b128 v[232:235], v213 offset:64
	ds_read_b128 v[216:219], v215 offset:64
	ds_read_b128 v[236:239], v213 offset:4672
	ds_read_b128 v[220:223], v215 offset:4672
	ds_read_b128 v[224:227], v215 offset:9280
	ds_read_b128 v[228:231], v215 offset:13888
	s_waitcnt vmcnt(4)
	ds_write_b128 v179, v[150:153] offset:36864
	ds_write_b128 v179, v[154:157] offset:36880
	ds_write_b128 v179, v[158:161] offset:36896
	ds_write_b128 v179, v[162:165] offset:36912
	global_load_dwordx4 v[150:153], v[248:249], off offset:1024
	global_load_dwordx4 v[154:157], v[248:249], off offset:1040
	global_load_dwordx4 v[158:161], v[248:249], off offset:1056
	global_load_dwordx4 v[162:165], v[248:249], off offset:1072
	s_waitcnt lgkmcnt(15)
	v_mfma_f32_32x32x16_f16 v[114:129], v[208:211], v[240:243], v[114:129]
	s_waitcnt lgkmcnt(15)
	v_mfma_f32_32x32x16_f16 v[98:113], v[174:177], v[240:243], v[98:113]
	s_waitcnt lgkmcnt(15)
	v_mfma_f32_32x32x16_f16 v[82:97], v[208:211], v[244:247], v[82:97]
	v_mfma_f32_32x32x16_f16 v[66:81], v[174:177], v[244:247], v[66:81]
	s_waitcnt lgkmcnt(15)
	v_mfma_f32_32x32x16_f16 v[50:65], v[208:211], v[200:203], v[50:65]
	v_mfma_f32_32x32x16_f16 v[34:49], v[174:177], v[200:203], v[34:49]
	s_waitcnt lgkmcnt(14)
	v_mfma_f32_32x32x16_f16 v[2:17], v[208:211], v[204:207], v[2:17]
	v_mfma_f32_32x32x16_f16 v[18:33], v[174:177], v[204:207], v[18:33]
	ds_read_b128 v[208:211], v213 offset:96
	ds_read_b128 v[240:243], v215 offset:96
	ds_read_b128 v[174:177], v213 offset:4704
	ds_read_b128 v[244:247], v215 offset:4704
	ds_read_b128 v[200:203], v215 offset:9312
	ds_read_b128 v[204:207], v215 offset:13920
	s_waitcnt lgkmcnt(14)
	v_mfma_f32_32x32x16_f16 v[114:129], v[232:235], v[216:219], v[114:129]
	s_waitcnt lgkmcnt(13)
	v_mfma_f32_32x32x16_f16 v[98:113], v[236:239], v[216:219], v[98:113]
	s_waitcnt lgkmcnt(12)
	v_mfma_f32_32x32x16_f16 v[82:97], v[232:235], v[220:223], v[82:97]
	v_mfma_f32_32x32x16_f16 v[66:81], v[236:239], v[220:223], v[66:81]
	s_waitcnt lgkmcnt(11)
	v_mfma_f32_32x32x16_f16 v[50:65], v[232:235], v[224:227], v[50:65]
	v_mfma_f32_32x32x16_f16 v[34:49], v[236:239], v[224:227], v[34:49]
	s_waitcnt lgkmcnt(10)
	v_mfma_f32_32x32x16_f16 v[2:17], v[232:235], v[228:231], v[2:17]
	v_mfma_f32_32x32x16_f16 v[18:33], v[236:239], v[228:231], v[18:33]
	s_waitcnt lgkmcnt(0)
	s_barrier
; DI f16v mfma32(h8v a, h8v b, f16v c) { return __builtin_amdgcn_mfma_f32_32x32x16_f16(a, b, c, 0, 0, 0); }
; template <bool GATHER>
; DI void gemm256_main(const h16* __restrict__ A, int lda, const int* __restrict__ idx, int m0,
;                      const h16* __restrict__ B, int ldb, int n0, int K, h16* lds, f16v (&acc)[4][2]) {
;     ...
;   for (int kt = 0; kt < nk; ++kt) {
;     const h16* As = lds + (kt & 1) * (512 * LDH);
;     const h16* Bs = As + 256 * LDH;
;     h16* Wn = lds + ((kt & 1) ^ 1) * (512 * LDH);
;     if (kt + 1 < nk) {
; #pragma unroll
;       for (int i = 0; i < 4; ++i) { *(u4v*)&Wn[lr * LDH + lc + 8 * i] = ra[i]; *(u4v*)&Wn[(256 + lr) * LDH + lc + 8 * i] = rb[i]; }
;     }
;     if (kt + 2 < nk) {
; #pragma unroll
;       for (int i = 0; i < 4; ++i) { ra[i] = *(const u4v*)(AP_ + 8 * i); rb[i] = *(const u4v*)(BP_ + 8 * i); }
;       ao += 64; bo += 64;
;     }
; #pragma unroll
;     for (int ks = 0; ks < 4; ++ks) {
;       h8v af[4], bf[2];
; #pragma unroll
;       for (int i = 0; i < 4; ++i) af[i] = *(const h8v*)&As[(wm * 128 + i * 32 + (lane & 31)) * LDH + ks * 16 + 8 * (lane >> 5)];
; #pragma unroll
;       for (int j = 0; j < 2; ++j) bf[j] = *(const h8v*)&Bs[(wn * 64 + j * 32 + (lane & 31)) * LDH + ks * 16 + 8 * (lane >> 5)];
; #pragma unroll
;       for (int i = 0; i < 4; ++i)
; #pragma unroll
;         for (int j = 0; j < 2; ++j) acc[i][j] = mfma32(bf[j], af[i], acc[i][j]);
;     }
;     __syncthreads();
	ds_read_b128 v[232:235], v214
	ds_read_b128 v[216:219], v212
	ds_read_b128 v[236:239], v214 offset:4608
	ds_read_b128 v[220:223], v212 offset:4608
	ds_read_b128 v[224:227], v212 offset:9216
	ds_read_b128 v[228:231], v212 offset:13824
	v_mfma_f32_32x32x16_f16 v[114:129], v[208:211], v[240:243], v[114:129]
	v_mfma_f32_32x32x16_f16 v[98:113], v[174:177], v[240:243], v[98:113]
	v_mfma_f32_32x32x16_f16 v[82:97], v[208:211], v[244:247], v[82:97]
	v_mfma_f32_32x32x16_f16 v[66:81], v[174:177], v[244:247], v[66:81]
	v_mfma_f32_32x32x16_f16 v[50:65], v[208:211], v[200:203], v[50:65]
	v_mfma_f32_32x32x16_f16 v[34:49], v[174:177], v[200:203], v[34:49]
	v_mfma_f32_32x32x16_f16 v[2:17], v[208:211], v[204:207], v[2:17]
	v_mfma_f32_32x32x16_f16 v[18:33], v[174:177], v[204:207], v[18:33]
	ds_read_b128 v[208:211], v214 offset:32
	ds_read_b128 v[240:243], v212 offset:32
	ds_read_b128 v[174:177], v214 offset:4640
	ds_read_b128 v[244:247], v212 offset:4640
	ds_read_b128 v[200:203], v212 offset:9248
	ds_read_b128 v[204:207], v212 offset:13856
	s_waitcnt vmcnt(4)
	ds_write_b128 v178, v[134:137]
	ds_write_b128 v178, v[138:141] offset:16
	ds_write_b128 v178, v[142:145] offset:32
	ds_write_b128 v178, v[146:149] offset:48
	global_load_dwordx4 v[134:137], v[130:131], off offset:1152
	global_load_dwordx4 v[138:141], v[130:131], off offset:1168
	global_load_dwordx4 v[142:145], v[130:131], off offset:1184
	global_load_dwordx4 v[146:149], v[130:131], off offset:1200
	s_waitcnt lgkmcnt(14)
	v_mfma_f32_32x32x16_f16 v[114:129], v[232:235], v[216:219], v[114:129]
	s_waitcnt lgkmcnt(13)
	v_mfma_f32_32x32x16_f16 v[98:113], v[236:239], v[216:219], v[98:113]
	s_waitcnt lgkmcnt(12)
	v_mfma_f32_32x32x16_f16 v[82:97], v[232:235], v[220:223], v[82:97]
	v_mfma_f32_32x32x16_f16 v[66:81], v[236:239], v[220:223], v[66:81]
	s_waitcnt lgkmcnt(11)
	v_mfma_f32_32x32x16_f16 v[50:65], v[232:235], v[224:227], v[50:65]
	v_mfma_f32_32x32x16_f16 v[34:49], v[236:239], v[224:227], v[34:49]
	s_waitcnt lgkmcnt(10)
	v_mfma_f32_32x32x16_f16 v[2:17], v[232:235], v[228:231], v[2:17]
	v_mfma_f32_32x32x16_f16 v[18:33], v[236:239], v[228:231], v[18:33]
	ds_read_b128 v[232:235], v214 offset:64
	ds_read_b128 v[216:219], v212 offset:64
	ds_read_b128 v[236:239], v214 offset:4672
	ds_read_b128 v[220:223], v212 offset:4672
	ds_read_b128 v[224:227], v212 offset:9280
	ds_read_b128 v[228:231], v212 offset:13888
	s_waitcnt vmcnt(4)
	ds_write_b128 v178, v[150:153] offset:36864
	ds_write_b128 v178, v[154:157] offset:36880
	ds_write_b128 v178, v[158:161] offset:36896
	ds_write_b128 v178, v[162:165] offset:36912
	global_load_dwordx4 v[150:153], v[248:249], off offset:1152
	global_load_dwordx4 v[154:157], v[248:249], off offset:1168
	global_load_dwordx4 v[158:161], v[248:249], off offset:1184
	global_load_dwordx4 v[162:165], v[248:249], off offset:1200
	s_waitcnt lgkmcnt(15)
	v_mfma_f32_32x32x16_f16 v[114:129], v[208:211], v[240:243], v[114:129]
	s_waitcnt lgkmcnt(15)
	v_mfma_f32_32x32x16_f16 v[98:113], v[174:177], v[240:243], v[98:113]
	s_waitcnt lgkmcnt(15)
	v_mfma_f32_32x32x16_f16 v[82:97], v[208:211], v[244:247], v[82:97]
	v_mfma_f32_32x32x16_f16 v[66:81], v[174:177], v[244:247], v[66:81]
	s_waitcnt lgkmcnt(15)
	v_mfma_f32_32x32x16_f16 v[50:65], v[208:211], v[200:203], v[50:65]
	v_mfma_f32_32x32x16_f16 v[34:49], v[174:177], v[200:203], v[34:49]
	s_waitcnt lgkmcnt(14)
	v_mfma_f32_32x32x16_f16 v[2:17], v[208:211], v[204:207], v[2:17]
	v_mfma_f32_32x32x16_f16 v[18:33], v[174:177], v[204:207], v[18:33]
	ds_read_b128 v[208:211], v214 offset:96
	ds_read_b128 v[240:243], v212 offset:96
	ds_read_b128 v[174:177], v214 offset:4704
	ds_read_b128 v[244:247], v212 offset:4704
	ds_read_b128 v[200:203], v212 offset:9312
	ds_read_b128 v[204:207], v212 offset:13920
	s_waitcnt lgkmcnt(14)
	v_mfma_f32_32x32x16_f16 v[114:129], v[232:235], v[216:219], v[114:129]
	s_waitcnt lgkmcnt(13)
	v_mfma_f32_32x32x16_f16 v[98:113], v[236:239], v[216:219], v[98:113]
	s_waitcnt lgkmcnt(12)
	v_mfma_f32_32x32x16_f16 v[82:97], v[232:235], v[220:223], v[82:97]
	v_mfma_f32_32x32x16_f16 v[66:81], v[236:239], v[220:223], v[66:81]
	s_waitcnt lgkmcnt(11)
	v_mfma_f32_32x32x16_f16 v[50:65], v[232:235], v[224:227], v[50:65]
	v_mfma_f32_32x32x16_f16 v[34:49], v[236:239], v[224:227], v[34:49]
	s_waitcnt lgkmcnt(10)
	v_mfma_f32_32x32x16_f16 v[2:17], v[232:235], v[228:231], v[2:17]
	v_mfma_f32_32x32x16_f16 v[18:33], v[236:239], v[228:231], v[18:33]
	s_waitcnt lgkmcnt(0)
	s_barrier
; DI f16v mfma32(h8v a, h8v b, f16v c) { return __builtin_amdgcn_mfma_f32_32x32x16_f16(a, b, c, 0, 0, 0); }
; template <bool GATHER>
; DI void gemm256_main(const h16* __restrict__ A, int lda, const int* __restrict__ idx, int m0,
;                      const h16* __restrict__ B, int ldb, int n0, int K, h16* lds, f16v (&acc)[4][2]) {
;     ...
;   for (int kt = 0; kt < nk; ++kt) {
;     const h16* As = lds + (kt & 1) * (512 * LDH);
;     const h16* Bs = As + 256 * LDH;
;     h16* Wn = lds + ((kt & 1) ^ 1) * (512 * LDH);
;     if (kt + 1 < nk) {
; #pragma unroll
;       for (int i = 0; i < 4; ++i) { *(u4v*)&Wn[lr * LDH + lc + 8 * i] = ra[i]; *(u4v*)&Wn[(256 + lr) * LDH + lc + 8 * i] = rb[i]; }
;     }
;     if (kt + 2 < nk) {
; #pragma unroll
;       for (int i = 0; i < 4; ++i) { ra[i] = *(const u4v*)(AP_ + 8 * i); rb[i] = *(const u4v*)(BP_ + 8 * i); }
;       ao += 64; bo += 64;
;     }
; #pragma unroll
;     for (int ks = 0; ks < 4; ++ks) {
;       h8v af[4], bf[2];
; #pragma unroll
;       for (int i = 0; i < 4; ++i) af[i] = *(const h8v*)&As[(wm * 128 + i * 32 + (lane & 31)) * LDH + ks * 16 + 8 * (lane >> 5)];
; #pragma unroll
;       for (int j = 0; j < 2; ++j) bf[j] = *(const h8v*)&Bs[(wn * 64 + j * 32 + (lane & 31)) * LDH + ks * 16 + 8 * (lane >> 5)];
; #pragma unroll
;       for (int i = 0; i < 4; ++i)
; #pragma unroll
;         for (int j = 0; j < 2; ++j) acc[i][j] = mfma32(bf[j], af[i], acc[i][j]);
;     }
;     __syncthreads();
	ds_read_b128 v[232:235], v213
	ds_read_b128 v[216:219], v215
	ds_read_b128 v[236:239], v213 offset:4608
	ds_read_b128 v[220:223], v215 offset:4608
	ds_read_b128 v[224:227], v215 offset:9216
	ds_read_b128 v[228:231], v215 offset:13824
	v_mfma_f32_32x32x16_f16 v[114:129], v[208:211], v[240:243], v[114:129]
	v_mfma_f32_32x32x16_f16 v[98:113], v[174:177], v[240:243], v[98:113]
	v_mfma_f32_32x32x16_f16 v[82:97], v[208:211], v[244:247], v[82:97]
	v_mfma_f32_32x32x16_f16 v[66:81], v[174:177], v[244:247], v[66:81]
	v_mfma_f32_32x32x16_f16 v[50:65], v[208:211], v[200:203], v[50:65]
	v_mfma_f32_32x32x16_f16 v[34:49], v[174:177], v[200:203], v[34:49]
	v_mfma_f32_32x32x16_f16 v[2:17], v[208:211], v[204:207], v[2:17]
	v_mfma_f32_32x32x16_f16 v[18:33], v[174:177], v[204:207], v[18:33]
	ds_read_b128 v[208:211], v213 offset:32
	ds_read_b128 v[240:243], v215 offset:32
	ds_read_b128 v[174:177], v213 offset:4640
	ds_read_b128 v[244:247], v215 offset:4640
	ds_read_b128 v[200:203], v215 offset:9248
	ds_read_b128 v[204:207], v215 offset:13856
	s_waitcnt vmcnt(4)
	ds_write_b128 v179, v[134:137]
	ds_write_b128 v179, v[138:141] offset:16
	ds_write_b128 v179, v[142:145] offset:32
	ds_write_b128 v179, v[146:149] offset:48
	global_load_dwordx4 v[134:137], v[130:131], off offset:1280
	global_load_dwordx4 v[138:141], v[130:131], off offset:1296
	global_load_dwordx4 v[142:145], v[130:131], off offset:1312
	global_load_dwordx4 v[146:149], v[130:131], off offset:1328
	s_waitcnt lgkmcnt(14)
	v_mfma_f32_32x32x16_f16 v[114:129], v[232:235], v[216:219], v[114:129]
	s_waitcnt lgkmcnt(13)
	v_mfma_f32_32x32x16_f16 v[98:113], v[236:239], v[216:219], v[98:113]
	s_waitcnt lgkmcnt(12)
	v_mfma_f32_32x32x16_f16 v[82:97], v[232:235], v[220:223], v[82:97]
	v_mfma_f32_32x32x16_f16 v[66:81], v[236:239], v[220:223], v[66:81]
	s_waitcnt lgkmcnt(11)
	v_mfma_f32_32x32x16_f16 v[50:65], v[232:235], v[224:227], v[50:65]
	v_mfma_f32_32x32x16_f16 v[34:49], v[236:239], v[224:227], v[34:49]
	s_waitcnt lgkmcnt(10)
	v_mfma_f32_32x32x16_f16 v[2:17], v[232:235], v[228:231], v[2:17]
	v_mfma_f32_32x32x16_f16 v[18:33], v[236:239], v[228:231], v[18:33]
	ds_read_b128 v[232:235], v213 offset:64
	ds_read_b128 v[216:219], v215 offset:64
	ds_read_b128 v[236:239], v213 offset:4672
	ds_read_b128 v[220:223], v215 offset:4672
	ds_read_b128 v[224:227], v215 offset:9280
	ds_read_b128 v[228:231], v215 offset:13888
	s_waitcnt vmcnt(4)
	ds_write_b128 v179, v[150:153] offset:36864
	ds_write_b128 v179, v[154:157] offset:36880
	ds_write_b128 v179, v[158:161] offset:36896
	ds_write_b128 v179, v[162:165] offset:36912
	global_load_dwordx4 v[150:153], v[248:249], off offset:1280
	global_load_dwordx4 v[154:157], v[248:249], off offset:1296
	global_load_dwordx4 v[158:161], v[248:249], off offset:1312
	global_load_dwordx4 v[162:165], v[248:249], off offset:1328
	s_waitcnt lgkmcnt(15)
	v_mfma_f32_32x32x16_f16 v[114:129], v[208:211], v[240:243], v[114:129]
	s_waitcnt lgkmcnt(15)
	v_mfma_f32_32x32x16_f16 v[98:113], v[174:177], v[240:243], v[98:113]
	s_waitcnt lgkmcnt(15)
	v_mfma_f32_32x32x16_f16 v[82:97], v[208:211], v[244:247], v[82:97]
	v_mfma_f32_32x32x16_f16 v[66:81], v[174:177], v[244:247], v[66:81]
	s_waitcnt lgkmcnt(15)
	v_mfma_f32_32x32x16_f16 v[50:65], v[208:211], v[200:203], v[50:65]
	v_mfma_f32_32x32x16_f16 v[34:49], v[174:177], v[200:203], v[34:49]
	s_waitcnt lgkmcnt(14)
	v_mfma_f32_32x32x16_f16 v[2:17], v[208:211], v[204:207], v[2:17]
	v_mfma_f32_32x32x16_f16 v[18:33], v[174:177], v[204:207], v[18:33]
	ds_read_b128 v[208:211], v213 offset:96
	ds_read_b128 v[240:243], v215 offset:96
	ds_read_b128 v[174:177], v213 offset:4704
	ds_read_b128 v[244:247], v215 offset:4704
	ds_read_b128 v[200:203], v215 offset:9312
	ds_read_b128 v[204:207], v215 offset:13920
	s_waitcnt lgkmcnt(14)
	v_mfma_f32_32x32x16_f16 v[114:129], v[232:235], v[216:219], v[114:129]
	s_waitcnt lgkmcnt(13)
	v_mfma_f32_32x32x16_f16 v[98:113], v[236:239], v[216:219], v[98:113]
	s_waitcnt lgkmcnt(12)
	v_mfma_f32_32x32x16_f16 v[82:97], v[232:235], v[220:223], v[82:97]
	v_mfma_f32_32x32x16_f16 v[66:81], v[236:239], v[220:223], v[66:81]
	s_waitcnt lgkmcnt(11)
	v_mfma_f32_32x32x16_f16 v[50:65], v[232:235], v[224:227], v[50:65]
	v_mfma_f32_32x32x16_f16 v[34:49], v[236:239], v[224:227], v[34:49]
	s_waitcnt lgkmcnt(10)
	v_mfma_f32_32x32x16_f16 v[2:17], v[232:235], v[228:231], v[2:17]
	v_mfma_f32_32x32x16_f16 v[18:33], v[236:239], v[228:231], v[18:33]
	s_waitcnt lgkmcnt(0)
	s_barrier
; DI f16v mfma32(h8v a, h8v b, f16v c) { return __builtin_amdgcn_mfma_f32_32x32x16_f16(a, b, c, 0, 0, 0); }
; template <bool GATHER>
; DI void gemm256_main(const h16* __restrict__ A, int lda, const int* __restrict__ idx, int m0,
;                      const h16* __restrict__ B, int ldb, int n0, int K, h16* lds, f16v (&acc)[4][2]) {
;     ...
;   for (int kt = 0; kt < nk; ++kt) {
;     const h16* As = lds + (kt & 1) * (512 * LDH);
;     const h16* Bs = As + 256 * LDH;
;     h16* Wn = lds + ((kt & 1) ^ 1) * (512 * LDH);
;     if (kt + 1 < nk) {
; #pragma unroll
;       for (int i = 0; i < 4; ++i) { *(u4v*)&Wn[lr * LDH + lc + 8 * i] = ra[i]; *(u4v*)&Wn[(256 + lr) * LDH + lc + 8 * i] = rb[i]; }
;     }
;     if (kt + 2 < nk) {
; #pragma unroll
;       for (int i = 0; i < 4; ++i) { ra[i] = *(const u4v*)(AP_ + 8 * i); rb[i] = *(const u4v*)(BP_ + 8 * i); }
;       ao += 64; bo += 64;
;     }
; #pragma unroll
;     for (int ks = 0; ks < 4; ++ks) {
;       h8v af[4], bf[2];
; #pragma unroll
;       for (int i = 0; i < 4; ++i) af[i] = *(const h8v*)&As[(wm * 128 + i * 32 + (lane & 31)) * LDH + ks * 16 + 8 * (lane >> 5)];
; #pragma unroll
;       for (int j = 0; j < 2; ++j) bf[j] = *(const h8v*)&Bs[(wn * 64 + j * 32 + (lane & 31)) * LDH + ks * 16 + 8 * (lane >> 5)];
; #pragma unroll
;       for (int i = 0; i < 4; ++i)
; #pragma unroll
;         for (int j = 0; j < 2; ++j) acc[i][j] = mfma32(bf[j], af[i], acc[i][j]);
;     }
;     __syncthreads();
	ds_read_b128 v[232:235], v214
	ds_read_b128 v[216:219], v212
	ds_read_b128 v[236:239], v214 offset:4608
	ds_read_b128 v[220:223], v212 offset:4608
	ds_read_b128 v[224:227], v212 offset:9216
	ds_read_b128 v[228:231], v212 offset:13824
	v_mfma_f32_32x32x16_f16 v[114:129], v[208:211], v[240:243], v[114:129]
	v_mfma_f32_32x32x16_f16 v[98:113], v[174:177], v[240:243], v[98:113]
	v_mfma_f32_32x32x16_f16 v[82:97], v[208:211], v[244:247], v[82:97]
	v_mfma_f32_32x32x16_f16 v[66:81], v[174:177], v[244:247], v[66:81]
	v_mfma_f32_32x32x16_f16 v[50:65], v[208:211], v[200:203], v[50:65]
	v_mfma_f32_32x32x16_f16 v[34:49], v[174:177], v[200:203], v[34:49]
	v_mfma_f32_32x32x16_f16 v[2:17], v[208:211], v[204:207], v[2:17]
	v_mfma_f32_32x32x16_f16 v[18:33], v[174:177], v[204:207], v[18:33]
	ds_read_b128 v[208:211], v214 offset:32
	ds_read_b128 v[240:243], v212 offset:32
	ds_read_b128 v[174:177], v214 offset:4640
	ds_read_b128 v[244:247], v212 offset:4640
	ds_read_b128 v[200:203], v212 offset:9248
	ds_read_b128 v[204:207], v212 offset:13856
	s_waitcnt vmcnt(4)
	ds_write_b128 v178, v[134:137]
	ds_write_b128 v178, v[138:141] offset:16
	ds_write_b128 v178, v[142:145] offset:32
	ds_write_b128 v178, v[146:149] offset:48
	global_load_dwordx4 v[134:137], v[130:131], off offset:1408
	global_load_dwordx4 v[138:141], v[130:131], off offset:1424
	global_load_dwordx4 v[142:145], v[130:131], off offset:1440
	global_load_dwordx4 v[146:149], v[130:131], off offset:1456
	s_waitcnt lgkmcnt(14)
	v_mfma_f32_32x32x16_f16 v[114:129], v[232:235], v[216:219], v[114:129]
	s_waitcnt lgkmcnt(13)
	v_mfma_f32_32x32x16_f16 v[98:113], v[236:239], v[216:219], v[98:113]
	s_waitcnt lgkmcnt(12)
	v_mfma_f32_32x32x16_f16 v[82:97], v[232:235], v[220:223], v[82:97]
	v_mfma_f32_32x32x16_f16 v[66:81], v[236:239], v[220:223], v[66:81]
	s_waitcnt lgkmcnt(11)
	v_mfma_f32_32x32x16_f16 v[50:65], v[232:235], v[224:227], v[50:65]
	v_mfma_f32_32x32x16_f16 v[34:49], v[236:239], v[224:227], v[34:49]
	s_waitcnt lgkmcnt(10)
	v_mfma_f32_32x32x16_f16 v[2:17], v[232:235], v[228:231], v[2:17]
	v_mfma_f32_32x32x16_f16 v[18:33], v[236:239], v[228:231], v[18:33]
	ds_read_b128 v[232:235], v214 offset:64
	ds_read_b128 v[216:219], v212 offset:64
	ds_read_b128 v[236:239], v214 offset:4672
	ds_read_b128 v[220:223], v212 offset:4672
	ds_read_b128 v[224:227], v212 offset:9280
	ds_read_b128 v[228:231], v212 offset:13888
	s_waitcnt vmcnt(4)
	ds_write_b128 v178, v[150:153] offset:36864
	ds_write_b128 v178, v[154:157] offset:36880
	ds_write_b128 v178, v[158:161] offset:36896
	ds_write_b128 v178, v[162:165] offset:36912
	global_load_dwordx4 v[150:153], v[248:249], off offset:1408
	global_load_dwordx4 v[154:157], v[248:249], off offset:1424
	global_load_dwordx4 v[158:161], v[248:249], off offset:1440
	global_load_dwordx4 v[162:165], v[248:249], off offset:1456
	s_waitcnt lgkmcnt(15)
	v_mfma_f32_32x32x16_f16 v[114:129], v[208:211], v[240:243], v[114:129]
	s_waitcnt lgkmcnt(15)
	v_mfma_f32_32x32x16_f16 v[98:113], v[174:177], v[240:243], v[98:113]
	s_waitcnt lgkmcnt(15)
	v_mfma_f32_32x32x16_f16 v[82:97], v[208:211], v[244:247], v[82:97]
	v_mfma_f32_32x32x16_f16 v[66:81], v[174:177], v[244:247], v[66:81]
	s_waitcnt lgkmcnt(15)
	v_mfma_f32_32x32x16_f16 v[50:65], v[208:211], v[200:203], v[50:65]
	v_mfma_f32_32x32x16_f16 v[34:49], v[174:177], v[200:203], v[34:49]
	s_waitcnt lgkmcnt(14)
	v_mfma_f32_32x32x16_f16 v[2:17], v[208:211], v[204:207], v[2:17]
	v_mfma_f32_32x32x16_f16 v[18:33], v[174:177], v[204:207], v[18:33]
	ds_read_b128 v[208:211], v214 offset:96
	ds_read_b128 v[240:243], v212 offset:96
	ds_read_b128 v[174:177], v214 offset:4704
	ds_read_b128 v[244:247], v212 offset:4704
	ds_read_b128 v[200:203], v212 offset:9312
	ds_read_b128 v[204:207], v212 offset:13920
	s_waitcnt lgkmcnt(14)
	v_mfma_f32_32x32x16_f16 v[114:129], v[232:235], v[216:219], v[114:129]
	s_waitcnt lgkmcnt(13)
	v_mfma_f32_32x32x16_f16 v[98:113], v[236:239], v[216:219], v[98:113]
	s_waitcnt lgkmcnt(12)
	v_mfma_f32_32x32x16_f16 v[82:97], v[232:235], v[220:223], v[82:97]
	v_mfma_f32_32x32x16_f16 v[66:81], v[236:239], v[220:223], v[66:81]
	s_waitcnt lgkmcnt(11)
	v_mfma_f32_32x32x16_f16 v[50:65], v[232:235], v[224:227], v[50:65]
	v_mfma_f32_32x32x16_f16 v[34:49], v[236:239], v[224:227], v[34:49]
	s_waitcnt lgkmcnt(10)
	v_mfma_f32_32x32x16_f16 v[2:17], v[232:235], v[228:231], v[2:17]
	v_mfma_f32_32x32x16_f16 v[18:33], v[236:239], v[228:231], v[18:33]
	s_waitcnt lgkmcnt(0)
	s_barrier
; DI f16v mfma32(h8v a, h8v b, f16v c) { return __builtin_amdgcn_mfma_f32_32x32x16_f16(a, b, c, 0, 0, 0); }
; template <bool GATHER>
; DI void gemm256_main(const h16* __restrict__ A, int lda, const int* __restrict__ idx, int m0,
;                      const h16* __restrict__ B, int ldb, int n0, int K, h16* lds, f16v (&acc)[4][2]) {
;     ...
;   for (int kt = 0; kt < nk; ++kt) {
;     const h16* As = lds + (kt & 1) * (512 * LDH);
;     const h16* Bs = As + 256 * LDH;
;     h16* Wn = lds + ((kt & 1) ^ 1) * (512 * LDH);
;     if (kt + 1 < nk) {
; #pragma unroll
;       for (int i = 0; i < 4; ++i) { *(u4v*)&Wn[lr * LDH + lc + 8 * i] = ra[i]; *(u4v*)&Wn[(256 + lr) * LDH + lc + 8 * i] = rb[i]; }
;     }
;     if (kt + 2 < nk) {
; #pragma unroll
;       for (int i = 0; i < 4; ++i) { ra[i] = *(const u4v*)(AP_ + 8 * i); rb[i] = *(const u4v*)(BP_ + 8 * i); }
;       ao += 64; bo += 64;
;     }
; #pragma unroll
;     for (int ks = 0; ks < 4; ++ks) {
;       h8v af[4], bf[2];
; #pragma unroll
;       for (int i = 0; i < 4; ++i) af[i] = *(const h8v*)&As[(wm * 128 + i * 32 + (lane & 31)) * LDH + ks * 16 + 8 * (lane >> 5)];
; #pragma unroll
;       for (int j = 0; j < 2; ++j) bf[j] = *(const h8v*)&Bs[(wn * 64 + j * 32 + (lane & 31)) * LDH + ks * 16 + 8 * (lane >> 5)];
; #pragma unroll
;       for (int i = 0; i < 4; ++i)
; #pragma unroll
;         for (int j = 0; j < 2; ++j) acc[i][j] = mfma32(bf[j], af[i], acc[i][j]);
;     }
;     __syncthreads();
	ds_read_b128 v[232:235], v213
	ds_read_b128 v[216:219], v215
	ds_read_b128 v[236:239], v213 offset:4608
	ds_read_b128 v[220:223], v215 offset:4608
	ds_read_b128 v[224:227], v215 offset:9216
	ds_read_b128 v[228:231], v215 offset:13824
	v_mfma_f32_32x32x16_f16 v[114:129], v[208:211], v[240:243], v[114:129]
	v_mfma_f32_32x32x16_f16 v[98:113], v[174:177], v[240:243], v[98:113]
	v_mfma_f32_32x32x16_f16 v[82:97], v[208:211], v[244:247], v[82:97]
	v_mfma_f32_32x32x16_f16 v[66:81], v[174:177], v[244:247], v[66:81]
	v_mfma_f32_32x32x16_f16 v[50:65], v[208:211], v[200:203], v[50:65]
	v_mfma_f32_32x32x16_f16 v[34:49], v[174:177], v[200:203], v[34:49]
	v_mfma_f32_32x32x16_f16 v[2:17], v[208:211], v[204:207], v[2:17]
	v_mfma_f32_32x32x16_f16 v[18:33], v[174:177], v[204:207], v[18:33]
	ds_read_b128 v[208:211], v213 offset:32
	ds_read_b128 v[240:243], v215 offset:32
	ds_read_b128 v[174:177], v213 offset:4640
	ds_read_b128 v[244:247], v215 offset:4640
	ds_read_b128 v[200:203], v215 offset:9248
	ds_read_b128 v[204:207], v215 offset:13856
	s_waitcnt vmcnt(4)
	ds_write_b128 v179, v[134:137]
	ds_write_b128 v179, v[138:141] offset:16
	ds_write_b128 v179, v[142:145] offset:32
	ds_write_b128 v179, v[146:149] offset:48
	global_load_dwordx4 v[134:137], v[130:131], off offset:1536
	global_load_dwordx4 v[138:141], v[130:131], off offset:1552
	global_load_dwordx4 v[142:145], v[130:131], off offset:1568
	global_load_dwordx4 v[146:149], v[130:131], off offset:1584
	s_waitcnt lgkmcnt(14)
	v_mfma_f32_32x32x16_f16 v[114:129], v[232:235], v[216:219], v[114:129]
	s_waitcnt lgkmcnt(13)
	v_mfma_f32_32x32x16_f16 v[98:113], v[236:239], v[216:219], v[98:113]
	s_waitcnt lgkmcnt(12)
	v_mfma_f32_32x32x16_f16 v[82:97], v[232:235], v[220:223], v[82:97]
	v_mfma_f32_32x32x16_f16 v[66:81], v[236:239], v[220:223], v[66:81]
	s_waitcnt lgkmcnt(11)
	v_mfma_f32_32x32x16_f16 v[50:65], v[232:235], v[224:227], v[50:65]
	v_mfma_f32_32x32x16_f16 v[34:49], v[236:239], v[224:227], v[34:49]
	s_waitcnt lgkmcnt(10)
	v_mfma_f32_32x32x16_f16 v[2:17], v[232:235], v[228:231], v[2:17]
	v_mfma_f32_32x32x16_f16 v[18:33], v[236:239], v[228:231], v[18:33]
	ds_read_b128 v[232:235], v213 offset:64
	ds_read_b128 v[216:219], v215 offset:64
	ds_read_b128 v[236:239], v213 offset:4672
	ds_read_b128 v[220:223], v215 offset:4672
	ds_read_b128 v[224:227], v215 offset:9280
	ds_read_b128 v[228:231], v215 offset:13888
	s_waitcnt vmcnt(4)
	ds_write_b128 v179, v[150:153] offset:36864
	ds_write_b128 v179, v[154:157] offset:36880
	ds_write_b128 v179, v[158:161] offset:36896
	ds_write_b128 v179, v[162:165] offset:36912
	global_load_dwordx4 v[150:153], v[248:249], off offset:1536
	global_load_dwordx4 v[154:157], v[248:249], off offset:1552
	global_load_dwordx4 v[158:161], v[248:249], off offset:1568
	global_load_dwordx4 v[162:165], v[248:249], off offset:1584
	s_waitcnt lgkmcnt(15)
	v_mfma_f32_32x32x16_f16 v[114:129], v[208:211], v[240:243], v[114:129]
	s_waitcnt lgkmcnt(15)
	v_mfma_f32_32x32x16_f16 v[98:113], v[174:177], v[240:243], v[98:113]
	s_waitcnt lgkmcnt(15)
	v_mfma_f32_32x32x16_f16 v[82:97], v[208:211], v[244:247], v[82:97]
	v_mfma_f32_32x32x16_f16 v[66:81], v[174:177], v[244:247], v[66:81]
	s_waitcnt lgkmcnt(15)
	v_mfma_f32_32x32x16_f16 v[50:65], v[208:211], v[200:203], v[50:65]
	v_mfma_f32_32x32x16_f16 v[34:49], v[174:177], v[200:203], v[34:49]
	s_waitcnt lgkmcnt(14)
	v_mfma_f32_32x32x16_f16 v[2:17], v[208:211], v[204:207], v[2:17]
	v_mfma_f32_32x32x16_f16 v[18:33], v[174:177], v[204:207], v[18:33]
	ds_read_b128 v[208:211], v213 offset:96
	ds_read_b128 v[240:243], v215 offset:96
	ds_read_b128 v[174:177], v213 offset:4704
	ds_read_b128 v[244:247], v215 offset:4704
	ds_read_b128 v[200:203], v215 offset:9312
	ds_read_b128 v[204:207], v215 offset:13920
	s_waitcnt lgkmcnt(14)
	v_mfma_f32_32x32x16_f16 v[114:129], v[232:235], v[216:219], v[114:129]
	s_waitcnt lgkmcnt(13)
	v_mfma_f32_32x32x16_f16 v[98:113], v[236:239], v[216:219], v[98:113]
	s_waitcnt lgkmcnt(12)
	v_mfma_f32_32x32x16_f16 v[82:97], v[232:235], v[220:223], v[82:97]
	v_mfma_f32_32x32x16_f16 v[66:81], v[236:239], v[220:223], v[66:81]
	s_waitcnt lgkmcnt(11)
	v_mfma_f32_32x32x16_f16 v[50:65], v[232:235], v[224:227], v[50:65]
	v_mfma_f32_32x32x16_f16 v[34:49], v[236:239], v[224:227], v[34:49]
	s_waitcnt lgkmcnt(10)
	v_mfma_f32_32x32x16_f16 v[2:17], v[232:235], v[228:231], v[2:17]
	v_mfma_f32_32x32x16_f16 v[18:33], v[236:239], v[228:231], v[18:33]
	s_waitcnt lgkmcnt(0)
	s_barrier
; DI f16v mfma32(h8v a, h8v b, f16v c) { return __builtin_amdgcn_mfma_f32_32x32x16_f16(a, b, c, 0, 0, 0); }
; template <bool GATHER>
; DI void gemm256_main(const h16* __restrict__ A, int lda, const int* __restrict__ idx, int m0,
;                      const h16* __restrict__ B, int ldb, int n0, int K, h16* lds, f16v (&acc)[4][2]) {
;     ...
;   for (int kt = 0; kt < nk; ++kt) {
;     const h16* As = lds + (kt & 1) * (512 * LDH);
;     const h16* Bs = As + 256 * LDH;
;     h16* Wn = lds + ((kt & 1) ^ 1) * (512 * LDH);
;     if (kt + 1 < nk) {
; #pragma unroll
;       for (int i = 0; i < 4; ++i) { *(u4v*)&Wn[lr * LDH + lc + 8 * i] = ra[i]; *(u4v*)&Wn[(256 + lr) * LDH + lc + 8 * i] = rb[i]; }
;     }
;     if (kt + 2 < nk) {
; #pragma unroll
;       for (int i = 0; i < 4; ++i) { ra[i] = *(const u4v*)(AP_ + 8 * i); rb[i] = *(const u4v*)(BP_ + 8 * i); }
;       ao += 64; bo += 64;
;     }
; #pragma unroll
;     for (int ks = 0; ks < 4; ++ks) {
;       h8v af[4], bf[2];
; #pragma unroll
;       for (int i = 0; i < 4; ++i) af[i] = *(const h8v*)&As[(wm * 128 + i * 32 + (lane & 31)) * LDH + ks * 16 + 8 * (lane >> 5)];
; #pragma unroll
;       for (int j = 0; j < 2; ++j) bf[j] = *(const h8v*)&Bs[(wn * 64 + j * 32 + (lane & 31)) * LDH + ks * 16 + 8 * (lane >> 5)];
; #pragma unroll
;       for (int i = 0; i < 4; ++i)
; #pragma unroll
;         for (int j = 0; j < 2; ++j) acc[i][j] = mfma32(bf[j], af[i], acc[i][j]);
;     }
;     __syncthreads();
	ds_read_b128 v[232:235], v214
	ds_read_b128 v[216:219], v212
	ds_read_b128 v[236:239], v214 offset:4608
	ds_read_b128 v[220:223], v212 offset:4608
	ds_read_b128 v[224:227], v212 offset:9216
	ds_read_b128 v[228:231], v212 offset:13824
	v_mfma_f32_32x32x16_f16 v[114:129], v[208:211], v[240:243], v[114:129]
	v_mfma_f32_32x32x16_f16 v[98:113], v[174:177], v[240:243], v[98:113]
	v_mfma_f32_32x32x16_f16 v[82:97], v[208:211], v[244:247], v[82:97]
	v_mfma_f32_32x32x16_f16 v[66:81], v[174:177], v[244:247], v[66:81]
	v_mfma_f32_32x32x16_f16 v[50:65], v[208:211], v[200:203], v[50:65]
	v_mfma_f32_32x32x16_f16 v[34:49], v[174:177], v[200:203], v[34:49]
	v_mfma_f32_32x32x16_f16 v[2:17], v[208:211], v[204:207], v[2:17]
	v_mfma_f32_32x32x16_f16 v[18:33], v[174:177], v[204:207], v[18:33]
	ds_read_b128 v[208:211], v214 offset:32
	ds_read_b128 v[240:243], v212 offset:32
	ds_read_b128 v[174:177], v214 offset:4640
	ds_read_b128 v[244:247], v212 offset:4640
	ds_read_b128 v[200:203], v212 offset:9248
	ds_read_b128 v[204:207], v212 offset:13856
	s_waitcnt vmcnt(4)
	ds_write_b128 v178, v[134:137]
	ds_write_b128 v178, v[138:141] offset:16
	ds_write_b128 v178, v[142:145] offset:32
	ds_write_b128 v178, v[146:149] offset:48
	global_load_dwordx4 v[134:137], v[130:131], off offset:1664
	global_load_dwordx4 v[138:141], v[130:131], off offset:1680
	global_load_dwordx4 v[142:145], v[130:131], off offset:1696
	global_load_dwordx4 v[146:149], v[130:131], off offset:1712
	s_waitcnt lgkmcnt(14)
	v_mfma_f32_32x32x16_f16 v[114:129], v[232:235], v[216:219], v[114:129]
	s_waitcnt lgkmcnt(13)
	v_mfma_f32_32x32x16_f16 v[98:113], v[236:239], v[216:219], v[98:113]
	s_waitcnt lgkmcnt(12)
	v_mfma_f32_32x32x16_f16 v[82:97], v[232:235], v[220:223], v[82:97]
	v_mfma_f32_32x32x16_f16 v[66:81], v[236:239], v[220:223], v[66:81]
	s_waitcnt lgkmcnt(11)
	v_mfma_f32_32x32x16_f16 v[50:65], v[232:235], v[224:227], v[50:65]
	v_mfma_f32_32x32x16_f16 v[34:49], v[236:239], v[224:227], v[34:49]
	s_waitcnt lgkmcnt(10)
	v_mfma_f32_32x32x16_f16 v[2:17], v[232:235], v[228:231], v[2:17]
	v_mfma_f32_32x32x16_f16 v[18:33], v[236:239], v[228:231], v[18:33]
	ds_read_b128 v[232:235], v214 offset:64
	ds_read_b128 v[216:219], v212 offset:64
	ds_read_b128 v[236:239], v214 offset:4672
	ds_read_b128 v[220:223], v212 offset:4672
	ds_read_b128 v[224:227], v212 offset:9280
	ds_read_b128 v[228:231], v212 offset:13888
	s_waitcnt vmcnt(4)
	ds_write_b128 v178, v[150:153] offset:36864
	ds_write_b128 v178, v[154:157] offset:36880
	ds_write_b128 v178, v[158:161] offset:36896
	ds_write_b128 v178, v[162:165] offset:36912
	global_load_dwordx4 v[150:153], v[248:249], off offset:1664
	global_load_dwordx4 v[154:157], v[248:249], off offset:1680
	global_load_dwordx4 v[158:161], v[248:249], off offset:1696
	global_load_dwordx4 v[162:165], v[248:249], off offset:1712
	s_waitcnt lgkmcnt(15)
	v_mfma_f32_32x32x16_f16 v[114:129], v[208:211], v[240:243], v[114:129]
	s_waitcnt lgkmcnt(15)
	v_mfma_f32_32x32x16_f16 v[98:113], v[174:177], v[240:243], v[98:113]
	s_waitcnt lgkmcnt(15)
	v_mfma_f32_32x32x16_f16 v[82:97], v[208:211], v[244:247], v[82:97]
	v_mfma_f32_32x32x16_f16 v[66:81], v[174:177], v[244:247], v[66:81]
	s_waitcnt lgkmcnt(15)
	v_mfma_f32_32x32x16_f16 v[50:65], v[208:211], v[200:203], v[50:65]
	v_mfma_f32_32x32x16_f16 v[34:49], v[174:177], v[200:203], v[34:49]
	s_waitcnt lgkmcnt(14)
	v_mfma_f32_32x32x16_f16 v[2:17], v[208:211], v[204:207], v[2:17]
	v_mfma_f32_32x32x16_f16 v[18:33], v[174:177], v[204:207], v[18:33]
	ds_read_b128 v[208:211], v214 offset:96
	ds_read_b128 v[240:243], v212 offset:96
	ds_read_b128 v[174:177], v214 offset:4704
	ds_read_b128 v[244:247], v212 offset:4704
	ds_read_b128 v[200:203], v212 offset:9312
	ds_read_b128 v[204:207], v212 offset:13920
	s_waitcnt lgkmcnt(14)
	v_mfma_f32_32x32x16_f16 v[114:129], v[232:235], v[216:219], v[114:129]
	s_waitcnt lgkmcnt(13)
	v_mfma_f32_32x32x16_f16 v[98:113], v[236:239], v[216:219], v[98:113]
	s_waitcnt lgkmcnt(12)
	v_mfma_f32_32x32x16_f16 v[82:97], v[232:235], v[220:223], v[82:97]
	v_mfma_f32_32x32x16_f16 v[66:81], v[236:239], v[220:223], v[66:81]
	s_waitcnt lgkmcnt(11)
	v_mfma_f32_32x32x16_f16 v[50:65], v[232:235], v[224:227], v[50:65]
	v_mfma_f32_32x32x16_f16 v[34:49], v[236:239], v[224:227], v[34:49]
	s_waitcnt lgkmcnt(10)
	v_mfma_f32_32x32x16_f16 v[2:17], v[232:235], v[228:231], v[2:17]
	v_mfma_f32_32x32x16_f16 v[18:33], v[236:239], v[228:231], v[18:33]
	s_waitcnt lgkmcnt(0)
	s_barrier
; DI f16v mfma32(h8v a, h8v b, f16v c) { return __builtin_amdgcn_mfma_f32_32x32x16_f16(a, b, c, 0, 0, 0); }
; template <bool GATHER>
; DI void gemm256_main(const h16* __restrict__ A, int lda, const int* __restrict__ idx, int m0,
;                      const h16* __restrict__ B, int ldb, int n0, int K, h16* lds, f16v (&acc)[4][2]) {
;     ...
;   for (int kt = 0; kt < nk; ++kt) {
;     const h16* As = lds + (kt & 1) * (512 * LDH);
;     const h16* Bs = As + 256 * LDH;
;     h16* Wn = lds + ((kt & 1) ^ 1) * (512 * LDH);
;     if (kt + 1 < nk) {
; #pragma unroll
;       for (int i = 0; i < 4; ++i) { *(u4v*)&Wn[lr * LDH + lc + 8 * i] = ra[i]; *(u4v*)&Wn[(256 + lr) * LDH + lc + 8 * i] = rb[i]; }
;     }
;     if (kt + 2 < nk) {
; #pragma unroll
;       for (int i = 0; i < 4; ++i) { ra[i] = *(const u4v*)(AP_ + 8 * i); rb[i] = *(const u4v*)(BP_ + 8 * i); }
;       ao += 64; bo += 64;
;     }
; #pragma unroll
;     for (int ks = 0; ks < 4; ++ks) {
;       h8v af[4], bf[2];
; #pragma unroll
;       for (int i = 0; i < 4; ++i) af[i] = *(const h8v*)&As[(wm * 128 + i * 32 + (lane & 31)) * LDH + ks * 16 + 8 * (lane >> 5)];
; #pragma unroll
;       for (int j = 0; j < 2; ++j) bf[j] = *(const h8v*)&Bs[(wn * 64 + j * 32 + (lane & 31)) * LDH + ks * 16 + 8 * (lane >> 5)];
; #pragma unroll
;       for (int i = 0; i < 4; ++i)
; #pragma unroll
;         for (int j = 0; j < 2; ++j) acc[i][j] = mfma32(bf[j], af[i], acc[i][j]);
;     }
;     __syncthreads();
	ds_read_b128 v[232:235], v213
	ds_read_b128 v[216:219], v215
	ds_read_b128 v[236:239], v213 offset:4608
	ds_read_b128 v[220:223], v215 offset:4608
	ds_read_b128 v[224:227], v215 offset:9216
	ds_read_b128 v[228:231], v215 offset:13824
	v_mfma_f32_32x32x16_f16 v[114:129], v[208:211], v[240:243], v[114:129]
	v_mfma_f32_32x32x16_f16 v[98:113], v[174:177], v[240:243], v[98:113]
	v_mfma_f32_32x32x16_f16 v[82:97], v[208:211], v[244:247], v[82:97]
	v_mfma_f32_32x32x16_f16 v[66:81], v[174:177], v[244:247], v[66:81]
	v_mfma_f32_32x32x16_f16 v[50:65], v[208:211], v[200:203], v[50:65]
	v_mfma_f32_32x32x16_f16 v[34:49], v[174:177], v[200:203], v[34:49]
	v_mfma_f32_32x32x16_f16 v[2:17], v[208:211], v[204:207], v[2:17]
	v_mfma_f32_32x32x16_f16 v[18:33], v[174:177], v[204:207], v[18:33]
	ds_read_b128 v[208:211], v213 offset:32
	ds_read_b128 v[240:243], v215 offset:32
	ds_read_b128 v[174:177], v213 offset:4640
	ds_read_b128 v[244:247], v215 offset:4640
	ds_read_b128 v[200:203], v215 offset:9248
	ds_read_b128 v[204:207], v215 offset:13856
	s_waitcnt vmcnt(4)
	ds_write_b128 v179, v[134:137]
	ds_write_b128 v179, v[138:141] offset:16
	ds_write_b128 v179, v[142:145] offset:32
	ds_write_b128 v179, v[146:149] offset:48
	global_load_dwordx4 v[134:137], v[130:131], off offset:1792
	global_load_dwordx4 v[138:141], v[130:131], off offset:1808
	global_load_dwordx4 v[142:145], v[130:131], off offset:1824
	global_load_dwordx4 v[146:149], v[130:131], off offset:1840
	s_waitcnt lgkmcnt(14)
	v_mfma_f32_32x32x16_f16 v[114:129], v[232:235], v[216:219], v[114:129]
	s_waitcnt lgkmcnt(13)
	v_mfma_f32_32x32x16_f16 v[98:113], v[236:239], v[216:219], v[98:113]
	s_waitcnt lgkmcnt(12)
	v_mfma_f32_32x32x16_f16 v[82:97], v[232:235], v[220:223], v[82:97]
	v_mfma_f32_32x32x16_f16 v[66:81], v[236:239], v[220:223], v[66:81]
	s_waitcnt lgkmcnt(11)
	v_mfma_f32_32x32x16_f16 v[50:65], v[232:235], v[224:227], v[50:65]
	v_mfma_f32_32x32x16_f16 v[34:49], v[236:239], v[224:227], v[34:49]
	s_waitcnt lgkmcnt(10)
	v_mfma_f32_32x32x16_f16 v[2:17], v[232:235], v[228:231], v[2:17]
	v_mfma_f32_32x32x16_f16 v[18:33], v[236:239], v[228:231], v[18:33]
	ds_read_b128 v[232:235], v213 offset:64
	ds_read_b128 v[216:219], v215 offset:64
	ds_read_b128 v[236:239], v213 offset:4672
	ds_read_b128 v[220:223], v215 offset:4672
	ds_read_b128 v[224:227], v215 offset:9280
	ds_read_b128 v[228:231], v215 offset:13888
	s_waitcnt vmcnt(4)
	ds_write_b128 v179, v[150:153] offset:36864
	ds_write_b128 v179, v[154:157] offset:36880
	ds_write_b128 v179, v[158:161] offset:36896
	ds_write_b128 v179, v[162:165] offset:36912
	global_load_dwordx4 v[150:153], v[248:249], off offset:1792
	global_load_dwordx4 v[154:157], v[248:249], off offset:1808
	global_load_dwordx4 v[158:161], v[248:249], off offset:1824
	global_load_dwordx4 v[162:165], v[248:249], off offset:1840
	s_waitcnt lgkmcnt(15)
	v_mfma_f32_32x32x16_f16 v[114:129], v[208:211], v[240:243], v[114:129]
	s_waitcnt lgkmcnt(15)
	v_mfma_f32_32x32x16_f16 v[98:113], v[174:177], v[240:243], v[98:113]
	s_waitcnt lgkmcnt(15)
	v_mfma_f32_32x32x16_f16 v[82:97], v[208:211], v[244:247], v[82:97]
	v_mfma_f32_32x32x16_f16 v[66:81], v[174:177], v[244:247], v[66:81]
	s_waitcnt lgkmcnt(15)
	v_mfma_f32_32x32x16_f16 v[50:65], v[208:211], v[200:203], v[50:65]
	v_mfma_f32_32x32x16_f16 v[34:49], v[174:177], v[200:203], v[34:49]
	s_waitcnt lgkmcnt(14)
	v_mfma_f32_32x32x16_f16 v[2:17], v[208:211], v[204:207], v[2:17]
	v_mfma_f32_32x32x16_f16 v[18:33], v[174:177], v[204:207], v[18:33]
	ds_read_b128 v[208:211], v213 offset:96
	ds_read_b128 v[240:243], v215 offset:96
	ds_read_b128 v[174:177], v213 offset:4704
	ds_read_b128 v[244:247], v215 offset:4704
	ds_read_b128 v[200:203], v215 offset:9312
	ds_read_b128 v[204:207], v215 offset:13920
	s_waitcnt lgkmcnt(14)
	v_mfma_f32_32x32x16_f16 v[114:129], v[232:235], v[216:219], v[114:129]
	s_waitcnt lgkmcnt(13)
	v_mfma_f32_32x32x16_f16 v[98:113], v[236:239], v[216:219], v[98:113]
	s_waitcnt lgkmcnt(12)
	v_mfma_f32_32x32x16_f16 v[82:97], v[232:235], v[220:223], v[82:97]
	v_mfma_f32_32x32x16_f16 v[66:81], v[236:239], v[220:223], v[66:81]
	s_waitcnt lgkmcnt(11)
	v_mfma_f32_32x32x16_f16 v[50:65], v[232:235], v[224:227], v[50:65]
	v_mfma_f32_32x32x16_f16 v[34:49], v[236:239], v[224:227], v[34:49]
	s_waitcnt lgkmcnt(10)
	v_mfma_f32_32x32x16_f16 v[2:17], v[232:235], v[228:231], v[2:17]
	v_mfma_f32_32x32x16_f16 v[18:33], v[236:239], v[228:231], v[18:33]
	s_waitcnt lgkmcnt(0)
	s_barrier
; DI f16v mfma32(h8v a, h8v b, f16v c) { return __builtin_amdgcn_mfma_f32_32x32x16_f16(a, b, c, 0, 0, 0); }
; template <bool GATHER>
; DI void gemm256_main(const h16* __restrict__ A, int lda, const int* __restrict__ idx, int m0,
;                      const h16* __restrict__ B, int ldb, int n0, int K, h16* lds, f16v (&acc)[4][2]) {
;     ...
;   for (int kt = 0; kt < nk; ++kt) {
;     const h16* As = lds + (kt & 1) * (512 * LDH);
;     const h16* Bs = As + 256 * LDH;
;     h16* Wn = lds + ((kt & 1) ^ 1) * (512 * LDH);
;     if (kt + 1 < nk) {
; #pragma unroll
;       for (int i = 0; i < 4; ++i) { *(u4v*)&Wn[lr * LDH + lc + 8 * i] = ra[i]; *(u4v*)&Wn[(256 + lr) * LDH + lc + 8 * i] = rb[i]; }
;     }
;     if (kt + 2 < nk) {
; #pragma unroll
;       for (int i = 0; i < 4; ++i) { ra[i] = *(const u4v*)(AP_ + 8 * i); rb[i] = *(const u4v*)(BP_ + 8 * i); }
;       ao += 64; bo += 64;
;     }
; #pragma unroll
;     for (int ks = 0; ks < 4; ++ks) {
;       h8v af[4], bf[2];
; #pragma unroll
;       for (int i = 0; i < 4; ++i) af[i] = *(const h8v*)&As[(wm * 128 + i * 32 + (lane & 31)) * LDH + ks * 16 + 8 * (lane >> 5)];
; #pragma unroll
;       for (int j = 0; j < 2; ++j) bf[j] = *(const h8v*)&Bs[(wn * 64 + j * 32 + (lane & 31)) * LDH + ks * 16 + 8 * (lane >> 5)];
; #pragma unroll
;       for (int i = 0; i < 4; ++i)
; #pragma unroll
;         for (int j = 0; j < 2; ++j) acc[i][j] = mfma32(bf[j], af[i], acc[i][j]);
;     }
;     __syncthreads();
	ds_read_b128 v[232:235], v214
	ds_read_b128 v[216:219], v212
	ds_read_b128 v[236:239], v214 offset:4608
	ds_read_b128 v[220:223], v212 offset:4608
	ds_read_b128 v[224:227], v212 offset:9216
	ds_read_b128 v[228:231], v212 offset:13824
	v_mfma_f32_32x32x16_f16 v[114:129], v[208:211], v[240:243], v[114:129]
	v_mfma_f32_32x32x16_f16 v[98:113], v[174:177], v[240:243], v[98:113]
	v_mfma_f32_32x32x16_f16 v[82:97], v[208:211], v[244:247], v[82:97]
	v_mfma_f32_32x32x16_f16 v[66:81], v[174:177], v[244:247], v[66:81]
	v_mfma_f32_32x32x16_f16 v[50:65], v[208:211], v[200:203], v[50:65]
	v_mfma_f32_32x32x16_f16 v[34:49], v[174:177], v[200:203], v[34:49]
	v_mfma_f32_32x32x16_f16 v[2:17], v[208:211], v[204:207], v[2:17]
	v_mfma_f32_32x32x16_f16 v[18:33], v[174:177], v[204:207], v[18:33]
	ds_read_b128 v[208:211], v214 offset:32
	ds_read_b128 v[240:243], v212 offset:32
	ds_read_b128 v[174:177], v214 offset:4640
	ds_read_b128 v[244:247], v212 offset:4640
	ds_read_b128 v[200:203], v212 offset:9248
	ds_read_b128 v[204:207], v212 offset:13856
	s_waitcnt vmcnt(4)
	ds_write_b128 v178, v[134:137]
	ds_write_b128 v178, v[138:141] offset:16
	ds_write_b128 v178, v[142:145] offset:32
	ds_write_b128 v178, v[146:149] offset:48
	global_load_dwordx4 v[134:137], v[130:131], off offset:1920
	global_load_dwordx4 v[138:141], v[130:131], off offset:1936
	global_load_dwordx4 v[142:145], v[130:131], off offset:1952
	global_load_dwordx4 v[146:149], v[130:131], off offset:1968
	s_waitcnt lgkmcnt(14)
	v_mfma_f32_32x32x16_f16 v[114:129], v[232:235], v[216:219], v[114:129]
	s_waitcnt lgkmcnt(13)
	v_mfma_f32_32x32x16_f16 v[98:113], v[236:239], v[216:219], v[98:113]
	s_waitcnt lgkmcnt(12)
	v_mfma_f32_32x32x16_f16 v[82:97], v[232:235], v[220:223], v[82:97]
	v_mfma_f32_32x32x16_f16 v[66:81], v[236:239], v[220:223], v[66:81]
	s_waitcnt lgkmcnt(11)
	v_mfma_f32_32x32x16_f16 v[50:65], v[232:235], v[224:227], v[50:65]
	v_mfma_f32_32x32x16_f16 v[34:49], v[236:239], v[224:227], v[34:49]
	s_waitcnt lgkmcnt(10)
	v_mfma_f32_32x32x16_f16 v[2:17], v[232:235], v[228:231], v[2:17]
	v_mfma_f32_32x32x16_f16 v[18:33], v[236:239], v[228:231], v[18:33]
	ds_read_b128 v[232:235], v214 offset:64
	ds_read_b128 v[216:219], v212 offset:64
	ds_read_b128 v[236:239], v214 offset:4672
	ds_read_b128 v[220:223], v212 offset:4672
	ds_read_b128 v[224:227], v212 offset:9280
	ds_read_b128 v[228:231], v212 offset:13888
	s_waitcnt vmcnt(4)
	ds_write_b128 v178, v[150:153] offset:36864
	ds_write_b128 v178, v[154:157] offset:36880
	ds_write_b128 v178, v[158:161] offset:36896
	ds_write_b128 v178, v[162:165] offset:36912
	global_load_dwordx4 v[150:153], v[248:249], off offset:1920
	global_load_dwordx4 v[154:157], v[248:249], off offset:1936
	global_load_dwordx4 v[158:161], v[248:249], off offset:1952
	global_load_dwordx4 v[162:165], v[248:249], off offset:1968
	s_waitcnt lgkmcnt(15)
	v_mfma_f32_32x32x16_f16 v[114:129], v[208:211], v[240:243], v[114:129]
	s_waitcnt lgkmcnt(15)
	v_mfma_f32_32x32x16_f16 v[98:113], v[174:177], v[240:243], v[98:113]
	s_waitcnt lgkmcnt(15)
	v_mfma_f32_32x32x16_f16 v[82:97], v[208:211], v[244:247], v[82:97]
	v_mfma_f32_32x32x16_f16 v[66:81], v[174:177], v[244:247], v[66:81]
	s_waitcnt lgkmcnt(15)
	v_mfma_f32_32x32x16_f16 v[50:65], v[208:211], v[200:203], v[50:65]
	v_mfma_f32_32x32x16_f16 v[34:49], v[174:177], v[200:203], v[34:49]
	s_waitcnt lgkmcnt(14)
	v_mfma_f32_32x32x16_f16 v[2:17], v[208:211], v[204:207], v[2:17]
	v_mfma_f32_32x32x16_f16 v[18:33], v[174:177], v[204:207], v[18:33]
	ds_read_b128 v[208:211], v214 offset:96
	ds_read_b128 v[240:243], v212 offset:96
	ds_read_b128 v[174:177], v214 offset:4704
	ds_read_b128 v[244:247], v212 offset:4704
	ds_read_b128 v[200:203], v212 offset:9312
	ds_read_b128 v[204:207], v212 offset:13920
	s_waitcnt lgkmcnt(14)
	v_mfma_f32_32x32x16_f16 v[114:129], v[232:235], v[216:219], v[114:129]
	s_waitcnt lgkmcnt(13)
	v_mfma_f32_32x32x16_f16 v[98:113], v[236:239], v[216:219], v[98:113]
	s_waitcnt lgkmcnt(12)
	v_mfma_f32_32x32x16_f16 v[82:97], v[232:235], v[220:223], v[82:97]
	v_mfma_f32_32x32x16_f16 v[66:81], v[236:239], v[220:223], v[66:81]
	s_waitcnt lgkmcnt(11)
	v_mfma_f32_32x32x16_f16 v[50:65], v[232:235], v[224:227], v[50:65]
	v_mfma_f32_32x32x16_f16 v[34:49], v[236:239], v[224:227], v[34:49]
	s_waitcnt lgkmcnt(10)
	v_mfma_f32_32x32x16_f16 v[2:17], v[232:235], v[228:231], v[2:17]
	v_mfma_f32_32x32x16_f16 v[18:33], v[236:239], v[228:231], v[18:33]
	s_waitcnt lgkmcnt(0)
	s_barrier
; DI f16v mfma32(h8v a, h8v b, f16v c) { return __builtin_amdgcn_mfma_f32_32x32x16_f16(a, b, c, 0, 0, 0); }
; template <bool GATHER>
; DI void gemm256_main(const h16* __restrict__ A, int lda, const int* __restrict__ idx, int m0,
;                      const h16* __restrict__ B, int ldb, int n0, int K, h16* lds, f16v (&acc)[4][2]) {
;     ...
;   for (int kt = 0; kt < nk; ++kt) {
;     const h16* As = lds + (kt & 1) * (512 * LDH);
;     const h16* Bs = As + 256 * LDH;
;     h16* Wn = lds + ((kt & 1) ^ 1) * (512 * LDH);
;     if (kt + 1 < nk) {
; #pragma unroll
;       for (int i = 0; i < 4; ++i) { *(u4v*)&Wn[lr * LDH + lc + 8 * i] = ra[i]; *(u4v*)&Wn[(256 + lr) * LDH + lc + 8 * i] = rb[i]; }
;     }
;     if (kt + 2 < nk) {
; #pragma unroll
;       for (int i = 0; i < 4; ++i) { ra[i] = *(const u4v*)(AP_ + 8 * i); rb[i] = *(const u4v*)(BP_ + 8 * i); }
;       ao += 64; bo += 64;
;     }
; #pragma unroll
;     for (int ks = 0; ks < 4; ++ks) {
;       h8v af[4], bf[2];
; #pragma unroll
;       for (int i = 0; i < 4; ++i) af[i] = *(const h8v*)&As[(wm * 128 + i * 32 + (lane & 31)) * LDH + ks * 16 + 8 * (lane >> 5)];
; #pragma unroll
;       for (int j = 0; j < 2; ++j) bf[j] = *(const h8v*)&Bs[(wn * 64 + j * 32 + (lane & 31)) * LDH + ks * 16 + 8 * (lane >> 5)];
; #pragma unroll
;       for (int i = 0; i < 4; ++i)
; #pragma unroll
;         for (int j = 0; j < 2; ++j) acc[i][j] = mfma32(bf[j], af[i], acc[i][j]);
;     }
;     __syncthreads();
	ds_read_b128 v[232:235], v213
	ds_read_b128 v[216:219], v215
	ds_read_b128 v[236:239], v213 offset:4608
	ds_read_b128 v[220:223], v215 offset:4608
	ds_read_b128 v[224:227], v215 offset:9216
	ds_read_b128 v[228:231], v215 offset:13824
	v_mfma_f32_32x32x16_f16 v[114:129], v[208:211], v[240:243], v[114:129]
	v_mfma_f32_32x32x16_f16 v[98:113], v[174:177], v[240:243], v[98:113]
	v_mfma_f32_32x32x16_f16 v[82:97], v[208:211], v[244:247], v[82:97]
	v_mfma_f32_32x32x16_f16 v[66:81], v[174:177], v[244:247], v[66:81]
	v_mfma_f32_32x32x16_f16 v[50:65], v[208:211], v[200:203], v[50:65]
	v_mfma_f32_32x32x16_f16 v[34:49], v[174:177], v[200:203], v[34:49]
	v_mfma_f32_32x32x16_f16 v[2:17], v[208:211], v[204:207], v[2:17]
	v_mfma_f32_32x32x16_f16 v[18:33], v[174:177], v[204:207], v[18:33]
	ds_read_b128 v[208:211], v213 offset:32
	ds_read_b128 v[240:243], v215 offset:32
	ds_read_b128 v[174:177], v213 offset:4640
	ds_read_b128 v[244:247], v215 offset:4640
	ds_read_b128 v[200:203], v215 offset:9248
	ds_read_b128 v[204:207], v215 offset:13856
	s_waitcnt vmcnt(4)
	ds_write_b128 v179, v[134:137]
	ds_write_b128 v179, v[138:141] offset:16
	ds_write_b128 v179, v[142:145] offset:32
	ds_write_b128 v179, v[146:149] offset:48
	s_waitcnt lgkmcnt(14)
	v_mfma_f32_32x32x16_f16 v[114:129], v[232:235], v[216:219], v[114:129]
	s_waitcnt lgkmcnt(13)
	v_mfma_f32_32x32x16_f16 v[98:113], v[236:239], v[216:219], v[98:113]
	s_waitcnt lgkmcnt(12)
	v_mfma_f32_32x32x16_f16 v[82:97], v[232:235], v[220:223], v[82:97]
	v_mfma_f32_32x32x16_f16 v[66:81], v[236:239], v[220:223], v[66:81]
	s_waitcnt lgkmcnt(11)
	v_mfma_f32_32x32x16_f16 v[50:65], v[232:235], v[224:227], v[50:65]
	v_mfma_f32_32x32x16_f16 v[34:49], v[236:239], v[224:227], v[34:49]
	s_waitcnt lgkmcnt(10)
	v_mfma_f32_32x32x16_f16 v[2:17], v[232:235], v[228:231], v[2:17]
	v_mfma_f32_32x32x16_f16 v[18:33], v[236:239], v[228:231], v[18:33]
	ds_read_b128 v[232:235], v213 offset:64
	ds_read_b128 v[216:219], v215 offset:64
	ds_read_b128 v[236:239], v213 offset:4672
	ds_read_b128 v[220:223], v215 offset:4672
	ds_read_b128 v[224:227], v215 offset:9280
	ds_read_b128 v[228:231], v215 offset:13888
	s_waitcnt vmcnt(0)
	ds_write_b128 v179, v[150:153] offset:36864
	ds_write_b128 v179, v[154:157] offset:36880
	ds_write_b128 v179, v[158:161] offset:36896
	ds_write_b128 v179, v[162:165] offset:36912
	s_waitcnt lgkmcnt(15)
	v_mfma_f32_32x32x16_f16 v[114:129], v[208:211], v[240:243], v[114:129]
	s_waitcnt lgkmcnt(15)
	v_mfma_f32_32x32x16_f16 v[98:113], v[174:177], v[240:243], v[98:113]
	s_waitcnt lgkmcnt(15)
	v_mfma_f32_32x32x16_f16 v[82:97], v[208:211], v[244:247], v[82:97]
	v_mfma_f32_32x32x16_f16 v[66:81], v[174:177], v[244:247], v[66:81]
	s_waitcnt lgkmcnt(15)
	v_mfma_f32_32x32x16_f16 v[50:65], v[208:211], v[200:203], v[50:65]
	v_mfma_f32_32x32x16_f16 v[34:49], v[174:177], v[200:203], v[34:49]
	s_waitcnt lgkmcnt(14)
	v_mfma_f32_32x32x16_f16 v[2:17], v[208:211], v[204:207], v[2:17]
	v_mfma_f32_32x32x16_f16 v[18:33], v[174:177], v[204:207], v[18:33]
	ds_read_b128 v[208:211], v213 offset:96
	ds_read_b128 v[240:243], v215 offset:96
	ds_read_b128 v[174:177], v213 offset:4704
	ds_read_b128 v[244:247], v215 offset:4704
	ds_read_b128 v[200:203], v215 offset:9312
	ds_read_b128 v[204:207], v215 offset:13920
	s_waitcnt lgkmcnt(14)
	v_mfma_f32_32x32x16_f16 v[114:129], v[232:235], v[216:219], v[114:129]
	s_waitcnt lgkmcnt(13)
	v_mfma_f32_32x32x16_f16 v[98:113], v[236:239], v[216:219], v[98:113]
	s_waitcnt lgkmcnt(12)
	v_mfma_f32_32x32x16_f16 v[82:97], v[232:235], v[220:223], v[82:97]
	v_mfma_f32_32x32x16_f16 v[66:81], v[236:239], v[220:223], v[66:81]
	s_waitcnt lgkmcnt(11)
	v_mfma_f32_32x32x16_f16 v[50:65], v[232:235], v[224:227], v[50:65]
	v_mfma_f32_32x32x16_f16 v[34:49], v[236:239], v[224:227], v[34:49]
	s_waitcnt lgkmcnt(10)
	v_mfma_f32_32x32x16_f16 v[2:17], v[232:235], v[228:231], v[2:17]
	v_mfma_f32_32x32x16_f16 v[18:33], v[236:239], v[228:231], v[18:33]
	s_waitcnt lgkmcnt(0)
	s_barrier
; DI f16v mfma32(h8v a, h8v b, f16v c) { return __builtin_amdgcn_mfma_f32_32x32x16_f16(a, b, c, 0, 0, 0); }
; template <bool GATHER>
; DI void gemm256_main(const h16* __restrict__ A, int lda, const int* __restrict__ idx, int m0,
;                      const h16* __restrict__ B, int ldb, int n0, int K, h16* lds, f16v (&acc)[4][2]) {
;     ...
; #pragma unroll
;     for (int ks = 0; ks < 4; ++ks) {
;       h8v af[4], bf[2];
; #pragma unroll
;       for (int i = 0; i < 4; ++i) af[i] = *(const h8v*)&As[(wm * 128 + i * 32 + (lane & 31)) * LDH + ks * 16 + 8 * (lane >> 5)];
; #pragma unroll
;       for (int j = 0; j < 2; ++j) bf[j] = *(const h8v*)&Bs[(wn * 64 + j * 32 + (lane & 31)) * LDH + ks * 16 + 8 * (lane >> 5)];
; #pragma unroll
;       for (int i = 0; i < 4; ++i)
; #pragma unroll
;         for (int j = 0; j < 2; ++j) acc[i][j] = mfma32(bf[j], af[i], acc[i][j]);
;     }
;     __syncthreads();
; DI void phase_p1(const Params& p, int l, int bid, int nb, int vb, int vnb, unsigned char* smem, unsigned char* smem_half) {
;     ...
;     gemm256_epilogue(acc, m0, n0, [&](int m, int n, f4v v0, f4v v1) {
;       const bool rope = (n >= 1024 && n < 2560) || (n >= 4352 && n < 4992);
;       if (rope) {
;         const int d = n & 31;
;         f4v c = *(const f4v*)&rc[(size_t)m * 32 + d], s = *(const f4v*)&rs[(size_t)m * 32 + d];
;         f4v o0 = v0 * c - v1 * s, o1 = v1 * c + v0 * s;
;         v0 = o0; v1 = o1;
	ds_read_b128 v[232:235], v214
	ds_read_b128 v[216:219], v212
	ds_read_b128 v[236:239], v214 offset:4608
	ds_read_b128 v[220:223], v212 offset:4608
	ds_read_b128 v[224:227], v212 offset:9216
	ds_read_b128 v[228:231], v212 offset:13824
	v_mfma_f32_32x32x16_f16 v[114:129], v[208:211], v[240:243], v[114:129]
	v_mfma_f32_32x32x16_f16 v[98:113], v[174:177], v[240:243], v[98:113]
	v_mfma_f32_32x32x16_f16 v[82:97], v[208:211], v[244:247], v[82:97]
	v_mfma_f32_32x32x16_f16 v[66:81], v[174:177], v[244:247], v[66:81]
	v_mfma_f32_32x32x16_f16 v[50:65], v[208:211], v[200:203], v[50:65]
	v_mfma_f32_32x32x16_f16 v[34:49], v[174:177], v[200:203], v[34:49]
	v_mfma_f32_32x32x16_f16 v[2:17], v[208:211], v[204:207], v[2:17]
	v_mfma_f32_32x32x16_f16 v[18:33], v[174:177], v[204:207], v[18:33]
	ds_read_b128 v[208:211], v214 offset:32
	ds_read_b128 v[240:243], v212 offset:32
	ds_read_b128 v[174:177], v214 offset:4640
	ds_read_b128 v[244:247], v212 offset:4640
	ds_read_b128 v[200:203], v212 offset:9248
	ds_read_b128 v[204:207], v212 offset:13856
	s_waitcnt lgkmcnt(10)
	v_mfma_f32_32x32x16_f16 v[114:129], v[232:235], v[216:219], v[114:129]
	s_waitcnt lgkmcnt(9)
	v_mfma_f32_32x32x16_f16 v[98:113], v[236:239], v[216:219], v[98:113]
	s_waitcnt lgkmcnt(8)
	v_mfma_f32_32x32x16_f16 v[82:97], v[232:235], v[220:223], v[82:97]
	v_mfma_f32_32x32x16_f16 v[66:81], v[236:239], v[220:223], v[66:81]
	s_waitcnt lgkmcnt(7)
	v_mfma_f32_32x32x16_f16 v[50:65], v[232:235], v[224:227], v[50:65]
	v_mfma_f32_32x32x16_f16 v[34:49], v[236:239], v[224:227], v[34:49]
	s_waitcnt lgkmcnt(6)
	v_mfma_f32_32x32x16_f16 v[2:17], v[232:235], v[228:231], v[2:17]
	v_mfma_f32_32x32x16_f16 v[18:33], v[236:239], v[228:231], v[18:33]
	ds_read_b128 v[232:235], v214 offset:64
	ds_read_b128 v[216:219], v212 offset:64
	ds_read_b128 v[236:239], v214 offset:4672
	ds_read_b128 v[220:223], v212 offset:4672
	ds_read_b128 v[224:227], v212 offset:9280
	ds_read_b128 v[228:231], v212 offset:13888
	s_waitcnt lgkmcnt(10)
	v_mfma_f32_32x32x16_f16 v[114:129], v[208:211], v[240:243], v[114:129]
	s_waitcnt lgkmcnt(9)
	v_mfma_f32_32x32x16_f16 v[98:113], v[174:177], v[240:243], v[98:113]
	s_waitcnt lgkmcnt(8)
	v_mfma_f32_32x32x16_f16 v[82:97], v[208:211], v[244:247], v[82:97]
	v_mfma_f32_32x32x16_f16 v[66:81], v[174:177], v[244:247], v[66:81]
	s_waitcnt lgkmcnt(7)
	v_mfma_f32_32x32x16_f16 v[50:65], v[208:211], v[200:203], v[50:65]
	v_mfma_f32_32x32x16_f16 v[34:49], v[174:177], v[200:203], v[34:49]
	s_waitcnt lgkmcnt(6)
	v_mfma_f32_32x32x16_f16 v[2:17], v[208:211], v[204:207], v[2:17]
	v_mfma_f32_32x32x16_f16 v[18:33], v[174:177], v[204:207], v[18:33]
	ds_read_b128 v[208:211], v214 offset:96
	ds_read_b128 v[240:243], v212 offset:96
	ds_read_b128 v[174:177], v214 offset:4704
	ds_read_b128 v[244:247], v212 offset:4704
	ds_read_b128 v[200:203], v212 offset:9312
	ds_read_b128 v[204:207], v212 offset:13920
	s_waitcnt lgkmcnt(10)
	v_mfma_f32_32x32x16_f16 v[114:129], v[232:235], v[216:219], v[114:129]
	s_waitcnt lgkmcnt(9)
	v_mfma_f32_32x32x16_f16 v[98:113], v[236:239], v[216:219], v[98:113]
	s_waitcnt lgkmcnt(8)
	v_mfma_f32_32x32x16_f16 v[82:97], v[232:235], v[220:223], v[82:97]
	v_mfma_f32_32x32x16_f16 v[66:81], v[236:239], v[220:223], v[66:81]
	s_waitcnt lgkmcnt(7)
	v_mfma_f32_32x32x16_f16 v[50:65], v[232:235], v[224:227], v[50:65]
	v_mfma_f32_32x32x16_f16 v[34:49], v[236:239], v[224:227], v[34:49]
	s_waitcnt lgkmcnt(6)
	v_mfma_f32_32x32x16_f16 v[2:17], v[232:235], v[228:231], v[2:17]
	v_mfma_f32_32x32x16_f16 v[18:33], v[236:239], v[228:231], v[18:33]
	s_waitcnt lgkmcnt(0)
	v_mfma_f32_32x32x16_f16 v[114:129], v[208:211], v[240:243], v[114:129]
	v_mfma_f32_32x32x16_f16 v[98:113], v[174:177], v[240:243], v[98:113]
	v_mfma_f32_32x32x16_f16 v[82:97], v[208:211], v[244:247], v[82:97]
	v_mfma_f32_32x32x16_f16 v[66:81], v[174:177], v[244:247], v[66:81]
	v_mfma_f32_32x32x16_f16 v[50:65], v[208:211], v[200:203], v[50:65]
	v_mfma_f32_32x32x16_f16 v[34:49], v[174:177], v[200:203], v[34:49]
	v_mfma_f32_32x32x16_f16 v[2:17], v[208:211], v[204:207], v[2:17]
	v_mfma_f32_32x32x16_f16 v[18:33], v[174:177], v[204:207], v[18:33]
	s_nop 15
	v_mov_b32_e32 v192, 0x7f800000
	v_mov_b32_e32 v193, 0x7fc00000
	v_mov_b32_e32 v194, 0xff800000
	v_mov_b32_e32 v204, 0x7fffec00
	v_mov_b32_e32 v205, 0xff7fc99e
	v_mov_b32_e32 v206, 0x840000
	v_mov_b32_e32 v207, 0xb00000
	v_mov_b32_e32 v208, 0xdc0000
	v_mov_b32_e32 v209, 0x1080000
	v_mov_b32_e32 v210, 0x1340000
	v_mov_b32_e32 v211, 0x420000
	v_mov_b32_e32 v212, 0x580000
	v_mov_b32_e32 v213, 0x6e0000
	v_mov_b32_e32 v214, 0x9a0000
	v_mov_b32_e32 v1, v180
	v_and_b32_e32 v132, 0xc0, v1
	v_subrev_u32_e32 v130, s6, v132
	v_add_u32_e32 v138, s18, v130
	v_add_u32_e32 v130, 0xfffff300, v138
	v_cmp_gt_u32_e32 vcc, s4, v130
	v_ashrrev_i32_e32 v130, 1, v1
	v_and_b32_e32 v130, 0xffffff80, v130
	v_and_or_b32 v131, v1, 31, s3
	v_add_u32_e32 v130, v131, v130
	v_lshrrev_b32_e32 v1, 3, v1
	v_ashrrev_i32_e32 v131, 31, v130
	s_cselect_b64 s[2:3], -1, 0
	v_and_b32_e32 v1, 4, v1
	s_or_b64 s[4:5], s[2:3], vcc
	v_lshlrev_b64 v[134:135], 5, v[130:131]
	s_and_saveexec_b64 s[2:3], s[4:5]
	s_cbranch_execz .LBB0_103
	v_or_b32_e32 v136, v134, v1
	v_mov_b32_e32 v137, v135
	v_readlane_b32 s8, v252, 62
	v_lshlrev_b64 v[136:137], 2, v[136:137]
	v_readlane_b32 s9, v252, 63
	s_nop 1
	v_lshl_add_u64 v[140:141], s[8:9], 0, v[136:137]
	v_readlane_b32 s8, v252, 60
	v_readlane_b32 s9, v252, 61
	global_load_dwordx4 v[140:143], v[140:141], off
	s_nop 0
	v_lshl_add_u64 v[136:137], s[8:9], 0, v[136:137]
	global_load_dwordx4 v[144:147], v[136:137], off
	s_waitcnt vmcnt(1)
	v_pk_mul_f32 v[136:137], v[100:101], v[142:143]
	v_pk_mul_f32 v[148:149], v[98:99], v[140:141]
	v_pk_mul_f32 v[142:143], v[116:117], v[142:143]
	v_pk_mul_f32 v[140:141], v[114:115], v[140:141]
	s_waitcnt vmcnt(0)
	v_pk_fma_f32 v[116:117], v[116:117], v[146:147], v[136:137] neg_lo:[0,0,1] neg_hi:[0,0,1]
	v_pk_fma_f32 v[114:115], v[114:115], v[144:145], v[148:149] neg_lo:[0,0,1] neg_hi:[0,0,1]
	v_pk_fma_f32 v[100:101], v[100:101], v[146:147], v[142:143]
	v_pk_fma_f32 v[98:99], v[98:99], v[144:145], v[140:141]

; DI int otid() { int t = threadIdx.x & 255; asm volatile("" : "+v"(t)); return t; }
; DI void phase_ln(const Params& p, int l, int which, int bid, int nb) {
;     ...
;   const int tid_ = otid(); const int lane = tid_ & 63, wv = tid_ >> 6;
;   f4v nx[4];
;   {
;     const int row0 = bid * 4 + wv;
; #pragma unroll
;     for (int i = 0; i < 4; ++i) nx[i] = *(const f4v*)&out[(size_t)row0 * DM + 256 * i + lane * 4];
;   }
;   for (int row = bid * 4 + wv; row < SEQ; row += nb * 4) {
;     ...
;       const float* rw = p.moe_router + (size_t)(l >> 1) * DM * 8;
;       float lg[8];
; #pragma unroll
;       for (int e = 0; e < 8; ++e) lg[e] = 0.f;
; #pragma unroll
;       for (int i = 0; i < 4; ++i)
; #pragma unroll
;         for (int k = 0; k < 4; ++k) {
;           const int c = 256 * i + lane * 4 + k;
;           const f4v r0 = *(const f4v*)&rw[(size_t)c * 8], r1 = *(const f4v*)&rw[(size_t)c * 8 + 4];
.LBB0_1405:
	s_or_b64 exec, exec, s[2:3]
	v_mov_b32_e32 v3, v181
	v_mov_b32_e32 v1, v182
	s_waitcnt lgkmcnt(0)
	s_barrier
	v_mov_b32_e32 v4, 0
	v_mov_b32_e32 v5, 0
	ds_write_b64 v0, v[4:5] offset:256
	ds_write_b64 v0, v[4:5] offset:264
	ds_write_b64 v0, v[4:5] offset:272
	ds_write_b64 v0, v[4:5] offset:280
	v_readlane_b32 s2, v252, 53
	v_readlane_b32 s3, v252, 54
	v_readlane_b32 s4, v255, 32
	v_lshlrev_b32_e32 v114, 4, v180
	v_bfe_u32 v132, v180, 1, 2
	s_lshl_b32 s4, s4, 14
	s_and_b32 s4, s4, 0x8000
	s_add_u32 s2, s2, s4
	s_addc_u32 s3, s3, 0
	v_add_u32_e32 v115, 0x2000, v114
	v_add_u32_e32 v134, 0x4000, v114
	v_add_u32_e32 v135, 0x6000, v114
	v_and_b32_e32 v133, 1, v180
	global_load_dwordx4 v[116:119], v114, s[2:3]
	global_load_dwordx4 v[120:123], v115, s[2:3]
	global_load_dwordx4 v[124:127], v134, s[2:3]
	global_load_dwordx4 v[128:131], v135, s[2:3]
	v_lshlrev_b32_e32 v132, 11, v132
	v_lshl_or_b32 v132, v133, 10, v132
	v_bfe_u32 v133, v180, 3, 6
	v_lshl_or_b32 v132, v133, 4, v132
	v_and_b32_e32 v140, 63, v180
	v_lshlrev_b32_e32 v140, 4, v140
	s_waitcnt vmcnt(3)
	ds_write_b128 v132, v[116:119] offset:4096
	s_waitcnt vmcnt(2)
	ds_write_b128 v132, v[120:123] offset:12288
	s_waitcnt vmcnt(1)
	ds_write_b128 v132, v[124:127] offset:20480
	s_waitcnt vmcnt(0)
	ds_write_b128 v132, v[128:131] offset:28672
	s_waitcnt lgkmcnt(0)
	s_barrier
	s_movk_i32 s2, 0x4000
	v_ashrrev_i32_e32 v2, 6, v1
	v_lshlrev_b32_e32 v4, 2, v3
	v_add_u32_e32 v50, v2, v4
	v_cmp_gt_i32_e32 vcc, s2, v50
	s_and_saveexec_b64 s[8:9], vcc
	s_cbranch_execz .LBB0_1418
	v_ashrrev_i32_e32 v51, 31, v50
	v_readlane_b32 s16, v252, 3
	v_and_b32_e32 v10, 63, v1
	v_lshlrev_b64 v[6:7], 12, v[50:51]
	v_readlane_b32 s18, v252, 5
	v_readlane_b32 s19, v252, 6
	v_lshlrev_b32_e32 v8, 4, v10
	v_mov_b32_e32 v9, v0
	v_lshl_add_u64 v[6:7], s[18:19], 0, v[6:7]
	v_lshl_add_u64 v[6:7], v[6:7], 0, v[8:9]
	global_load_dwordx4 v[18:21], v[6:7], off offset:3072
	global_load_dwordx4 v[22:25], v[6:7], off offset:2048
	global_load_dwordx4 v[26:29], v[6:7], off offset:1024
	global_load_dwordx4 v[30:33], v[6:7], off
	v_and_b32_e32 v1, 64, v196
	v_add_u32_e32 v5, 64, v1
	v_xor_b32_e32 v1, 32, v196
	v_cmp_lt_i32_e32 vcc, v1, v5
	v_xor_b32_e32 v6, 16, v196
	v_readlane_b32 s4, v255, 30
	v_cndmask_b32_e32 v1, v196, v1, vcc
	v_cmp_lt_i32_e32 vcc, v6, v5
	v_readlane_b32 s6, v255, 32
	v_readlane_b32 s5, v255, 31
	v_cndmask_b32_e32 v6, v196, v6, vcc
	v_lshlrev_b32_e32 v51, 2, v6
	v_xor_b32_e32 v6, 8, v196
	v_cmp_lt_i32_e32 vcc, v6, v5
	s_lshl_b32 s2, s6, 10
	s_mov_b32 s3, s5
	v_cndmask_b32_e32 v6, v196, v6, vcc
	v_lshlrev_b32_e32 v80, 2, v6
	v_xor_b32_e32 v6, 4, v196
	v_readlane_b32 s40, v252, 27
	v_cmp_lt_i32_e32 vcc, v6, v5
	s_lshl_b64 s[4:5], s[2:3], 2
	v_readlane_b32 s54, v252, 41
	v_cndmask_b32_e32 v6, v196, v6, vcc
	v_readlane_b32 s55, v252, 42
	s_add_u32 s2, s54, s4
	v_lshlrev_b32_e32 v81, 2, v6
	v_xor_b32_e32 v6, 2, v196
	v_readlane_b32 s52, v252, 39
	s_addc_u32 s3, s55, s5
	v_cmp_lt_i32_e32 vcc, v6, v5
	v_readlane_b32 s41, v252, 28
	v_readlane_b32 s42, v252, 29
	v_readlane_b32 s43, v252, 30
	v_readlane_b32 s44, v252, 31
	v_readlane_b32 s45, v252, 32
	v_readlane_b32 s46, v252, 33
	v_readlane_b32 s47, v252, 34
	v_readlane_b32 s48, v252, 35
	v_readlane_b32 s49, v252, 36
	v_readlane_b32 s50, v252, 37
	v_readlane_b32 s51, v252, 38
	v_readlane_b32 s53, v252, 40
	s_add_u32 s4, s52, s4
	v_cndmask_b32_e32 v6, v196, v6, vcc
	s_addc_u32 s5, s53, s5
	v_lshlrev_b32_e32 v82, 2, v6
	v_xor_b32_e32 v6, 1, v196
	s_lshl_b32 s6, s6, 14
	v_readlane_b32 s40, v252, 43
	v_cmp_lt_i32_e32 vcc, v6, v5
	s_and_b32 s6, s6, 0x8000
	v_readlane_b32 s50, v252, 53
	v_cndmask_b32_e32 v5, v196, v6, vcc
	v_lshl_add_u64 v[56:57], s[2:3], 0, v[8:9]
	v_lshlrev_b32_e32 v6, 7, v10
	v_readlane_b32 s51, v252, 54
	s_add_u32 s2, s50, s6
	v_lshl_add_u64 v[52:53], s[18:19], 0, v[8:9]
	v_lshl_add_u64 v[54:55], s[4:5], 0, v[8:9]
	s_addc_u32 s3, s51, 0
	v_mov_b32_e32 v7, v0
	v_or_b32_e32 v8, 0x2000, v6
	v_lshlrev_b32_e32 v83, 2, v5
	v_lshl_add_u64 v[58:59], s[2:3], 0, v[6:7]
	v_lshl_add_u64 v[60:61], s[2:3], 0, v[8:9]
	v_or_b32_e32 v8, 0x4000, v6
	v_or_b32_e32 v6, 0x6000, v6
	v_lshlrev_b32_e32 v5, 1, v2
	v_lshl_add_u64 v[64:65], s[2:3], 0, v[8:9]
	v_lshl_add_u64 v[68:69], s[2:3], 0, v[6:7]
	s_mov_b64 s[2:3], 0x6040
	v_lshl_add_u32 v3, v3, 3, v5
	v_lshl_add_u64 v[70:71], v[58:59], 0, s[2:3]
	v_or_b32_e32 v72, 1, v3
	v_readlane_b32 s2, v255, 18
	v_ashrrev_i32_e32 v3, 31, v2
	v_ashrrev_i32_e32 v5, 31, v4
	v_readlane_b32 s3, v255, 19
	v_add3_u32 v6, s2, v2, v4
	v_lshl_add_u64 v[2:3], v[2:3], 0, v[4:5]
	v_lshlrev_b64 v[76:77], 12, v[2:3]
	v_lshlrev_b64 v[2:3], 11, v[2:3]
	v_readlane_b32 s2, v255, 16
	s_mov_b64 s[4:5], 0x2040
	v_ashrrev_i32_e32 v7, 31, v6
	v_lshl_or_b32 v2, v10, 3, v2
	v_readlane_b32 s3, v255, 17
	v_cmp_eq_u32_e64 s[38:39], 0, v10
	v_lshl_add_u64 v[62:63], v[58:59], 0, s[4:5]
	s_mov_b64 s[4:5], 0x4040
	v_lshlrev_b64 v[74:75], 12, v[6:7]
	v_lshl_add_u64 v[78:79], s[2:3], 0, v[2:3]
	s_waitcnt vmcnt(3)
	v_mov_b64_e32 v[2:3], v[18:19]
	s_waitcnt vmcnt(2)
	v_mov_b64_e32 v[6:7], v[22:23]
	s_waitcnt vmcnt(1)
	v_mov_b64_e32 v[10:11], v[26:27]
	s_waitcnt vmcnt(0)
	v_mov_b64_e32 v[14:15], v[30:31]
	v_lshlrev_b32_e32 v1, 2, v1
	v_lshl_add_u64 v[66:67], v[58:59], 0, s[4:5]
	s_mov_b64 s[34:35], 0
	v_mov_b64_e32 v[4:5], v[20:21]
	v_mov_b64_e32 v[8:9], v[24:25]
	v_mov_b64_e32 v[12:13], v[28:29]
	v_mov_b64_e32 v[16:17], v[32:33]
	v_readlane_b32 s7, v255, 33
	v_readlane_b32 s17, v252, 4
	v_readlane_b32 s20, v252, 7
	v_readlane_b32 s21, v252, 8
	v_readlane_b32 s22, v252, 9
	v_readlane_b32 s23, v252, 10
	v_readlane_b32 s41, v252, 44
	v_readlane_b32 s42, v252, 45
	v_readlane_b32 s43, v252, 46
	v_readlane_b32 s44, v252, 47
	v_readlane_b32 s45, v252, 48
	v_readlane_b32 s46, v252, 49
	v_readlane_b32 s47, v252, 50
	v_readlane_b32 s48, v252, 51
	v_readlane_b32 s49, v252, 52
	v_readlane_b32 s52, v252, 55
	v_readlane_b32 s53, v252, 56
	v_readlane_b32 s54, v252, 57
	v_readlane_b32 s55, v252, 58
	s_branch .LBB0_1411

; DI void phase_ln(const Params& p, int l, int which, int bid, int nb) {
;     ...
;     float s = 0.f;
; #pragma unroll
;     for (int i = 0; i < 16; ++i) s += v[i];
;     const float mu = wave_sum(s) * (1.f / 1024.f);
;     float vs = 0.f;
; #pragma unroll
;     for (int i = 0; i < 16; ++i) { const float d = v[i] - mu; vs += d * d; }
;     const float rstd = rsqrtf(wave_sum(vs) * (1.f / 1024.f) + 1e-5f);
; #pragma unroll
;     for (int i = 0; i < 4; ++i) {
;       const int c = 256 * i + lane * 4;
;       const f4v w4 = *(const f4v*)&lw[c], b4 = *(const f4v*)&lb[c];
;       f4v y;
; #pragma unroll
;       for (int e = 0; e < 4; ++e) { y[e] = (v[4 * i + e] - mu) * rstd * w4[e] + b4[e]; v[4 * i + e] = y[e]; }
;       *(f4v*)&out[(size_t)row * DM + c] = y;
;       st_h4(&x16[(size_t)row * DM + c], y);
;     }
.LBB0_1413:
	s_or_b64 exec, exec, s[2:3]
	v_add_f32_e32 v34, 0, v30
	v_add_f32_e32 v34, v31, v34
	v_add_f32_e32 v34, v32, v34
	v_add_f32_e32 v34, v33, v34
	v_add_f32_e32 v34, v26, v34
	v_add_f32_e32 v34, v27, v34
	v_add_f32_e32 v34, v28, v34
	v_add_f32_e32 v34, v29, v34
	v_add_f32_e32 v34, v22, v34
	v_add_f32_e32 v34, v23, v34
	v_add_f32_e32 v34, v24, v34
	v_add_f32_e32 v34, v25, v34
	v_add_f32_e32 v34, v18, v34
	v_add_f32_e32 v34, v19, v34
	v_add_f32_e32 v34, v20, v34
	v_add_f32_e32 v34, v21, v34
	ds_bpermute_b32 v35, v1, v34
	v_readlane_b32 s2, v255, 34
	v_readlane_b32 s3, v255, 35
	s_waitcnt lgkmcnt(0)
	v_add_f32_e32 v34, v34, v35
	ds_bpermute_b32 v35, v51, v34
	s_waitcnt lgkmcnt(0)
	v_add_f32_e32 v34, v34, v35
	ds_bpermute_b32 v35, v80, v34
	s_waitcnt lgkmcnt(0)
	v_add_f32_e32 v34, v34, v35
	ds_bpermute_b32 v35, v81, v34
	s_waitcnt lgkmcnt(0)
	v_add_f32_e32 v34, v34, v35
	ds_bpermute_b32 v35, v82, v34
	s_waitcnt lgkmcnt(0)
	v_add_f32_e32 v42, v34, v35
	global_load_dwordx4 v[34:37], v[54:55], off
	global_load_dwordx4 v[38:41], v[56:57], off
	ds_bpermute_b32 v43, v83, v42
	s_waitcnt lgkmcnt(0)
	v_add_f32_e32 v42, v42, v43
	v_mul_f32_e32 v42, 0x3a800000, v42
	v_pk_add_f32 v[30:31], v[30:31], v[42:43] op_sel_hi:[1,0] neg_lo:[0,1] neg_hi:[0,1]
	v_pk_add_f32 v[32:33], v[32:33], v[42:43] op_sel_hi:[1,0] neg_lo:[0,1] neg_hi:[0,1]
	v_pk_add_f32 v[86:87], v[18:19], v[42:43] op_sel_hi:[1,0] neg_lo:[0,1] neg_hi:[0,1]
	v_pk_mul_f32 v[18:19], v[30:31], v[30:31]
	v_pk_add_f32 v[44:45], v[26:27], v[42:43] op_sel_hi:[1,0] neg_lo:[0,1] neg_hi:[0,1]
	v_pk_add_f32 v[46:47], v[28:29], v[42:43] op_sel_hi:[1,0] neg_lo:[0,1] neg_hi:[0,1]
	v_pk_add_f32 v[48:49], v[22:23], v[42:43] op_sel_hi:[1,0] neg_lo:[0,1] neg_hi:[0,1]
	v_pk_add_f32 v[84:85], v[24:25], v[42:43] op_sel_hi:[1,0] neg_lo:[0,1] neg_hi:[0,1]
	v_pk_add_f32 v[42:43], v[20:21], v[42:43] op_sel_hi:[1,0] neg_lo:[0,1] neg_hi:[0,1]
	v_pk_mul_f32 v[20:21], v[32:33], v[32:33]
	v_add_f32_e32 v18, v18, v19
	v_add_f32_e32 v18, v20, v18
	v_pk_mul_f32 v[22:23], v[44:45], v[44:45]
	v_add_f32_e32 v18, v21, v18
	v_add_f32_e32 v18, v22, v18
	v_pk_mul_f32 v[24:25], v[46:47], v[46:47]
	v_add_f32_e32 v18, v23, v18
	v_add_f32_e32 v18, v24, v18
	v_pk_mul_f32 v[26:27], v[48:49], v[48:49]
	v_add_f32_e32 v18, v25, v18
	v_add_f32_e32 v18, v26, v18
	v_pk_mul_f32 v[28:29], v[84:85], v[84:85]
	v_add_f32_e32 v18, v27, v18
	v_add_f32_e32 v18, v28, v18
	v_pk_mul_f32 v[88:89], v[86:87], v[86:87]
	v_add_f32_e32 v18, v29, v18
	v_add_f32_e32 v18, v88, v18
	v_pk_mul_f32 v[90:91], v[42:43], v[42:43]
	v_add_f32_e32 v18, v89, v18
	v_add_f32_e32 v18, v90, v18
	v_add_f32_e32 v18, v91, v18
	ds_bpermute_b32 v19, v1, v18
	v_lshl_add_u64 v[88:89], v[52:53], 0, v[76:77]
	s_waitcnt lgkmcnt(0)
	v_add_f32_e32 v18, v18, v19
	ds_bpermute_b32 v19, v51, v18
	s_waitcnt lgkmcnt(0)
	v_add_f32_e32 v18, v18, v19
	ds_bpermute_b32 v19, v80, v18
	s_waitcnt lgkmcnt(0)
	v_add_f32_e32 v18, v18, v19
	ds_bpermute_b32 v19, v81, v18
	s_waitcnt lgkmcnt(0)
	v_add_f32_e32 v18, v18, v19
	ds_bpermute_b32 v19, v82, v18
	s_waitcnt lgkmcnt(0)
	v_add_f32_e32 v18, v18, v19
	ds_bpermute_b32 v19, v83, v18
	s_waitcnt lgkmcnt(0)
	v_add_f32_e32 v18, v18, v19
	v_fmamk_f32 v18, v18, 0x3a800000, v189
	v_mul_f32_e32 v19, 0x4b800000, v18
	v_cmp_gt_f32_e32 vcc, s97, v18
	s_nop 1
	v_cndmask_b32_e32 v18, v18, v19, vcc
	v_rsq_f32_e32 v18, v18
	s_nop 0
	v_mul_f32_e32 v19, 0x45800000, v18
	v_cndmask_b32_e32 v90, v18, v19, vcc
	v_pk_mul_f32 v[18:19], v[30:31], v[90:91] op_sel_hi:[1,0]
	v_pk_mul_f32 v[20:21], v[32:33], v[90:91] op_sel_hi:[1,0]
	s_waitcnt vmcnt(0)
	v_pk_fma_f32 v[26:27], v[34:35], v[18:19], v[38:39]
	v_pk_fma_f32 v[28:29], v[36:37], v[20:21], v[40:41]
	v_cvt_pk_f16_f32 v18, v26, v27
	v_cvt_pk_f16_f32 v19, v28, v29
	global_store_dwordx4 v[88:89], v[26:29], off
	global_store_dwordx2 v[78:79], v[18:19], off offset:-1536
	global_load_dwordx4 v[18:21], v[54:55], off offset:1024
	s_nop 0
	global_load_dwordx4 v[22:25], v[56:57], off offset:1024
	v_pk_mul_f32 v[30:31], v[44:45], v[90:91] op_sel_hi:[1,0]
	v_pk_mul_f32 v[32:33], v[46:47], v[90:91] op_sel_hi:[1,0]
	v_pk_mul_f32 v[34:35], v[48:49], v[90:91] op_sel_hi:[1,0]
	v_pk_mul_f32 v[36:37], v[84:85], v[90:91] op_sel_hi:[1,0]
	v_pk_mul_f32 v[38:39], v[86:87], v[90:91] op_sel_hi:[1,0]
	v_pk_mul_f32 v[40:41], v[42:43], v[90:91] op_sel_hi:[1,0]
	s_andn2_b64 vcc, exec, s[2:3]
	s_waitcnt vmcnt(0)
	v_pk_fma_f32 v[30:31], v[18:19], v[30:31], v[22:23]
	v_pk_fma_f32 v[32:33], v[20:21], v[32:33], v[24:25]
	v_cvt_pk_f16_f32 v18, v30, v31
	v_cvt_pk_f16_f32 v19, v32, v33
	global_store_dwordx4 v[88:89], v[30:33], off offset:1024
	global_store_dwordx2 v[78:79], v[18:19], off offset:-1024
	global_load_dwordx4 v[18:21], v[54:55], off offset:2048
	s_nop 0
	global_load_dwordx4 v[22:25], v[56:57], off offset:2048
	s_waitcnt vmcnt(0)
	v_pk_fma_f32 v[18:19], v[18:19], v[34:35], v[22:23]
	v_pk_fma_f32 v[20:21], v[20:21], v[36:37], v[24:25]
	v_cvt_pk_f16_f32 v22, v18, v19
	v_cvt_pk_f16_f32 v23, v20, v21
	global_store_dwordx4 v[88:89], v[18:21], off offset:2048
	global_store_dwordx2 v[78:79], v[22:23], off offset:-512
	global_load_dwordx4 v[22:25], v[54:55], off offset:3072
	s_nop 0
	global_load_dwordx4 v[34:37], v[56:57], off offset:3072
	s_waitcnt vmcnt(0)
	v_pk_fma_f32 v[22:23], v[22:23], v[38:39], v[34:35]
	v_pk_fma_f32 v[24:25], v[24:25], v[40:41], v[36:37]
	v_cvt_pk_f16_f32 v34, v22, v23
	v_cvt_pk_f16_f32 v35, v24, v25
	global_store_dwordx4 v[88:89], v[22:25], off offset:3072
	global_store_dwordx2 v[78:79], v[34:35], off
	s_cbranch_vccnz .LBB0_1410
; DI void phase_ln(const Params& p, int l, int which, int bid, int nb) {
;     ...
; #pragma unroll
;       for (int i = 0; i < 4; ++i)
; #pragma unroll
;         for (int k = 0; k < 4; ++k) {
;           const int c = 256 * i + lane * 4 + k;
;           const f4v r0 = *(const f4v*)&rw[(size_t)c * 8], r1 = *(const f4v*)&rw[(size_t)c * 8 + 4];
;           const float xv = v[4 * i + k];
; #pragma unroll
;           for (int e = 0; e < 4; ++e) { lg[e] += xv * r0[e]; lg[4 + e] += xv * r1[e]; }
;         }
; #pragma unroll
;       for (int e = 0; e < 8; ++e) lg[e] = wave_sum(lg[e]);
	ds_read_b128 v[42:45], v140 offset:7168
	ds_read_b128 v[34:37], v140 offset:6144
	ds_read_b128 v[46:49], v140 offset:5120
	ds_read_b128 v[38:41], v140 offset:4096
	s_waitcnt lgkmcnt(1)
	v_fma_f32 v86, v26, v46, 0
	v_fma_f32 v85, v26, v47, 0
	v_fma_f32 v84, v26, v48, 0
	v_fma_f32 v73, v26, v49, 0
	s_waitcnt lgkmcnt(0)
	v_fma_f32 v88, v26, v40, 0
	v_fma_f32 v87, v26, v41, 0
	v_fmac_f32_e32 v86, v27, v42
	v_fmac_f32_e32 v85, v27, v43
	v_fmac_f32_e32 v84, v27, v44
	v_fmac_f32_e32 v73, v27, v45
	ds_read_b128 v[90:93], v140 offset:11264
	ds_read_b128 v[40:43], v140 offset:10240
	ds_read_b128 v[94:97], v140 offset:9216
	ds_read_b128 v[44:47], v140 offset:8192
	v_fmac_f32_e32 v88, v27, v36
	v_fmac_f32_e32 v87, v27, v37
	v_pk_fma_f32 v[36:37], v[26:27], v[38:39], 0 op_sel_hi:[0,1,0]
	v_pk_fma_f32 v[26:27], v[26:27], v[34:35], v[36:37] op_sel:[1,0,0]
	s_waitcnt lgkmcnt(1)
	v_fmac_f32_e32 v86, v28, v94
	v_fmac_f32_e32 v85, v28, v95
	v_fmac_f32_e32 v84, v28, v96
	v_fmac_f32_e32 v73, v28, v97
	s_waitcnt lgkmcnt(0)
	v_fmac_f32_e32 v88, v28, v46
	v_fmac_f32_e32 v87, v28, v47
	v_fmac_f32_e32 v86, v29, v90
	v_fmac_f32_e32 v85, v29, v91
	v_fmac_f32_e32 v84, v29, v92
	v_fmac_f32_e32 v73, v29, v93
	ds_read_b128 v[90:93], v140 offset:15360
	ds_read_b128 v[46:49], v140 offset:14336
	ds_read_b128 v[94:97], v140 offset:13312
	ds_read_b128 v[98:101], v140 offset:12288
	v_fmac_f32_e32 v88, v29, v42
	v_fmac_f32_e32 v87, v29, v43
	v_pk_fma_f32 v[26:27], v[28:29], v[44:45], v[26:27] op_sel_hi:[0,1,1]
	v_pk_fma_f32 v[26:27], v[28:29], v[40:41], v[26:27] op_sel:[1,0,0]
	s_waitcnt lgkmcnt(1)
	v_fmac_f32_e32 v86, v30, v94
	v_fmac_f32_e32 v85, v30, v95
	v_fmac_f32_e32 v84, v30, v96
	v_fmac_f32_e32 v73, v30, v97
	s_waitcnt lgkmcnt(0)
	v_fmac_f32_e32 v88, v30, v100
	v_fmac_f32_e32 v87, v30, v101
	v_fmac_f32_e32 v86, v31, v90
	v_fmac_f32_e32 v85, v31, v91
	v_fmac_f32_e32 v84, v31, v92
	v_fmac_f32_e32 v73, v31, v93
	ds_read_b128 v[90:93], v140 offset:19456
	ds_read_b128 v[94:97], v140 offset:18432
	ds_read_b128 v[100:103], v140 offset:17408
	ds_read_b128 v[104:107], v140 offset:16384
	v_fmac_f32_e32 v88, v31, v48
	v_fmac_f32_e32 v87, v31, v49
	v_pk_fma_f32 v[26:27], v[30:31], v[98:99], v[26:27] op_sel_hi:[0,1,1]
	v_pk_fma_f32 v[26:27], v[30:31], v[46:47], v[26:27] op_sel:[1,0,0]
	s_waitcnt lgkmcnt(1)
	v_fmac_f32_e32 v86, v32, v100
	v_fmac_f32_e32 v85, v32, v101
	v_fmac_f32_e32 v84, v32, v102
	v_fmac_f32_e32 v73, v32, v103
	s_waitcnt lgkmcnt(0)
	v_fmac_f32_e32 v88, v32, v106
	v_fmac_f32_e32 v87, v32, v107
	v_fmac_f32_e32 v86, v33, v90
	v_fmac_f32_e32 v85, v33, v91
	v_fmac_f32_e32 v84, v33, v92
	v_fmac_f32_e32 v73, v33, v93
	ds_read_b128 v[90:93], v140 offset:23552
	ds_read_b128 v[100:103], v140 offset:22528
	ds_read_b128 v[106:109], v140 offset:21504
	ds_read_b128 v[110:113], v140 offset:20480
	v_pk_fma_f32 v[26:27], v[32:33], v[104:105], v[26:27] op_sel_hi:[0,1,1]
	v_pk_fma_f32 v[26:27], v[32:33], v[94:95], v[26:27] op_sel:[1,0,0]
	v_fmac_f32_e32 v88, v33, v96
	v_fmac_f32_e32 v87, v33, v97
	s_waitcnt lgkmcnt(1)
	v_fmac_f32_e32 v86, v18, v106
	s_waitcnt lgkmcnt(0)
	v_pk_fma_f32 v[26:27], v[18:19], v[110:111], v[26:27] op_sel_hi:[0,1,1]
	v_pk_fma_f32 v[46:47], v[18:19], v[100:101], v[26:27] op_sel:[1,0,0]
	ds_read_b128 v[34:37], v140 offset:27648
	ds_read_b128 v[26:29], v140 offset:26624
	ds_read_b128 v[38:41], v140 offset:25600
	ds_read_b128 v[30:33], v140 offset:24576
	v_fmac_f32_e32 v85, v18, v107
	v_fmac_f32_e32 v84, v18, v108
	v_fmac_f32_e32 v73, v18, v109
	v_fmac_f32_e32 v88, v18, v112
	v_fmac_f32_e32 v87, v18, v113
	v_fmac_f32_e32 v86, v19, v90
	v_fmac_f32_e32 v85, v19, v91
	v_fmac_f32_e32 v84, v19, v92
	v_fmac_f32_e32 v73, v19, v93
	v_fmac_f32_e32 v88, v19, v102
	v_fmac_f32_e32 v87, v19, v103
	s_waitcnt lgkmcnt(1)
	v_fmac_f32_e32 v86, v20, v38
	v_fmac_f32_e32 v85, v20, v39
	v_fmac_f32_e32 v84, v20, v40
	v_fmac_f32_e32 v73, v20, v41
	s_waitcnt lgkmcnt(0)
	v_fmac_f32_e32 v88, v20, v32
	v_fmac_f32_e32 v87, v20, v33
	v_fmac_f32_e32 v86, v21, v34
	v_fmac_f32_e32 v85, v21, v35
	v_fmac_f32_e32 v84, v21, v36
	v_fmac_f32_e32 v73, v21, v37
	ds_read_b128 v[40:43], v140 offset:31744
	ds_read_b128 v[32:35], v140 offset:30720
	ds_read_b128 v[90:93], v140 offset:29696
	ds_read_b128 v[36:39], v140 offset:28672
	v_fmac_f32_e32 v88, v21, v28
	v_fmac_f32_e32 v87, v21, v29
	v_pk_fma_f32 v[18:19], v[20:21], v[30:31], v[46:47] op_sel_hi:[0,1,1]
	v_pk_fma_f32 v[18:19], v[20:21], v[26:27], v[18:19] op_sel:[1,0,0]
	s_waitcnt lgkmcnt(1)
	v_fmac_f32_e32 v86, v22, v90
	v_fmac_f32_e32 v85, v22, v91
	v_fmac_f32_e32 v84, v22, v92
	v_fmac_f32_e32 v73, v22, v93
	s_waitcnt lgkmcnt(0)
	v_fmac_f32_e32 v88, v22, v38
	v_fmac_f32_e32 v87, v22, v39
	v_fmac_f32_e32 v86, v23, v40
	v_fmac_f32_e32 v85, v23, v41
	v_fmac_f32_e32 v84, v23, v42
	v_fmac_f32_e32 v73, v23, v43
	ds_read_b128 v[90:93], v140 offset:35840
	ds_read_b128 v[38:41], v140 offset:34816
	ds_read_b128 v[94:97], v140 offset:33792
	ds_read_b128 v[42:45], v140 offset:32768
	v_pk_fma_f32 v[18:19], v[22:23], v[36:37], v[18:19] op_sel_hi:[0,1,1]
	v_fmac_f32_e32 v88, v23, v34
	v_fmac_f32_e32 v87, v23, v35
	v_pk_fma_f32 v[18:19], v[22:23], v[32:33], v[18:19] op_sel:[1,0,0]
	s_waitcnt lgkmcnt(1)
	v_fmac_f32_e32 v86, v24, v94
	v_fmac_f32_e32 v85, v24, v95
	s_waitcnt lgkmcnt(0)
	v_fmac_f32_e32 v88, v24, v44
	v_fmac_f32_e32 v84, v24, v96
	v_fmac_f32_e32 v87, v24, v45
	v_fmac_f32_e32 v73, v24, v97
	v_pk_fma_f32 v[18:19], v[24:25], v[42:43], v[18:19] op_sel_hi:[0,1,1]
	v_fmac_f32_e32 v86, v25, v90
	v_fmac_f32_e32 v85, v25, v91
	v_fmac_f32_e32 v88, v25, v40
	v_fmac_f32_e32 v84, v25, v92
	v_fmac_f32_e32 v87, v25, v41
	v_fmac_f32_e32 v73, v25, v93
	v_pk_fma_f32 v[18:19], v[24:25], v[38:39], v[18:19] op_sel:[1,0,0]
	ds_bpermute_b32 v20, v1, v18
	ds_bpermute_b32 v21, v1, v19
	ds_bpermute_b32 v22, v1, v88
	ds_bpermute_b32 v24, v1, v87
	ds_bpermute_b32 v26, v1, v86
	ds_bpermute_b32 v28, v1, v85
	ds_bpermute_b32 v30, v1, v84
	ds_bpermute_b32 v32, v1, v73
	s_waitcnt lgkmcnt(6)
; DI void phase_ln(const Params& p, int l, int which, int bid, int nb) {
;     ...
;       for (int e = 0; e < 8; ++e) lg[e] = wave_sum(lg[e]);
;       if (lane == 0) {
;         int i1 = 0; float b1 = lg[0];
; #pragma unroll
;         for (int e = 1; e < 8; ++e) if (lg[e] > b1) { b1 = lg[e]; i1 = e; }
;         int i2 = -1; float b2 = -3.4e38f;
; #pragma unroll
;         for (int e = 0; e < 8; ++e) if (e != i1 && lg[e] > b2) { b2 = lg[e]; i2 = e; }
	v_pk_add_f32 v[18:19], v[18:19], v[20:21]
	s_waitcnt lgkmcnt(5)
	v_add_f32_e32 v22, v88, v22
	s_waitcnt lgkmcnt(4)
	v_add_f32_e32 v24, v87, v24
	s_waitcnt lgkmcnt(3)
	v_add_f32_e32 v26, v86, v26
	s_waitcnt lgkmcnt(2)
	v_add_f32_e32 v28, v85, v28
	s_waitcnt lgkmcnt(1)
	v_add_f32_e32 v30, v84, v30
	s_waitcnt lgkmcnt(0)
	v_add_f32_e32 v32, v73, v32
	ds_bpermute_b32 v20, v51, v18
	ds_bpermute_b32 v21, v51, v19
	ds_bpermute_b32 v23, v51, v22
	ds_bpermute_b32 v25, v51, v24
	ds_bpermute_b32 v27, v51, v26
	ds_bpermute_b32 v29, v51, v28
	ds_bpermute_b32 v31, v51, v30
	ds_bpermute_b32 v33, v51, v32
	s_waitcnt lgkmcnt(6)
	v_pk_add_f32 v[18:19], v[18:19], v[20:21]
	s_waitcnt lgkmcnt(5)
	v_add_f32_e32 v22, v22, v23
	s_waitcnt lgkmcnt(4)
	v_add_f32_e32 v24, v24, v25
	s_waitcnt lgkmcnt(3)
	v_add_f32_e32 v26, v26, v27
	s_waitcnt lgkmcnt(2)
	v_add_f32_e32 v28, v28, v29
	s_waitcnt lgkmcnt(1)
	v_add_f32_e32 v30, v30, v31
	s_waitcnt lgkmcnt(0)
	v_add_f32_e32 v32, v32, v33
	ds_bpermute_b32 v20, v80, v18
	ds_bpermute_b32 v21, v80, v19
	ds_bpermute_b32 v23, v80, v22
	ds_bpermute_b32 v25, v80, v24
	ds_bpermute_b32 v27, v80, v26
	ds_bpermute_b32 v29, v80, v28
	ds_bpermute_b32 v31, v80, v30
	ds_bpermute_b32 v33, v80, v32
	s_waitcnt lgkmcnt(6)
	v_pk_add_f32 v[18:19], v[18:19], v[20:21]
	s_waitcnt lgkmcnt(5)
	v_add_f32_e32 v22, v22, v23
	s_waitcnt lgkmcnt(4)
	v_add_f32_e32 v24, v24, v25
	s_waitcnt lgkmcnt(3)
	v_add_f32_e32 v26, v26, v27
	s_waitcnt lgkmcnt(2)
	v_add_f32_e32 v28, v28, v29
	s_waitcnt lgkmcnt(1)
	v_add_f32_e32 v30, v30, v31
	s_waitcnt lgkmcnt(0)
	v_add_f32_e32 v32, v32, v33
	ds_bpermute_b32 v20, v81, v18
	ds_bpermute_b32 v21, v81, v19
	ds_bpermute_b32 v23, v81, v22
	ds_bpermute_b32 v25, v81, v24
	ds_bpermute_b32 v27, v81, v26
	ds_bpermute_b32 v29, v81, v28
	ds_bpermute_b32 v31, v81, v30
	ds_bpermute_b32 v33, v81, v32
	s_waitcnt lgkmcnt(6)
	v_pk_add_f32 v[18:19], v[18:19], v[20:21]
	s_waitcnt lgkmcnt(5)
	v_add_f32_e32 v22, v22, v23
	s_waitcnt lgkmcnt(4)
	v_add_f32_e32 v24, v24, v25
	s_waitcnt lgkmcnt(3)
	v_add_f32_e32 v26, v26, v27
	s_waitcnt lgkmcnt(2)
	v_add_f32_e32 v28, v28, v29
	s_waitcnt lgkmcnt(1)
	v_add_f32_e32 v30, v30, v31
	s_waitcnt lgkmcnt(0)
	v_add_f32_e32 v32, v32, v33
	ds_bpermute_b32 v20, v82, v18
	ds_bpermute_b32 v21, v82, v19
	ds_bpermute_b32 v23, v82, v22
	ds_bpermute_b32 v25, v82, v24
	ds_bpermute_b32 v27, v82, v26
	ds_bpermute_b32 v29, v82, v28
	ds_bpermute_b32 v31, v82, v30
	ds_bpermute_b32 v33, v82, v32
	s_waitcnt lgkmcnt(6)
	v_pk_add_f32 v[18:19], v[18:19], v[20:21]
	s_waitcnt lgkmcnt(5)
	v_add_f32_e32 v22, v22, v23
	s_waitcnt lgkmcnt(4)
	v_add_f32_e32 v24, v24, v25
	s_waitcnt lgkmcnt(3)
	v_add_f32_e32 v26, v26, v27
	s_waitcnt lgkmcnt(2)
	v_add_f32_e32 v28, v28, v29
	s_waitcnt lgkmcnt(1)
	v_add_f32_e32 v30, v30, v31
	s_waitcnt lgkmcnt(0)
	v_add_f32_e32 v32, v32, v33
	ds_bpermute_b32 v20, v83, v18
	ds_bpermute_b32 v21, v83, v19
	ds_bpermute_b32 v23, v83, v22
	ds_bpermute_b32 v25, v83, v24
	ds_bpermute_b32 v27, v83, v26
	ds_bpermute_b32 v29, v83, v28
	ds_bpermute_b32 v31, v83, v30
	ds_bpermute_b32 v33, v83, v32
	s_and_saveexec_b64 s[16:17], s[38:39]
	s_cbranch_execz .LBB0_1409
	s_waitcnt lgkmcnt(6)
	v_pk_add_f32 v[20:21], v[18:19], v[20:21]
	s_waitcnt lgkmcnt(5)
	v_add_f32_e32 v22, v22, v23
	v_cmp_gt_f32_e32 vcc, v21, v20
	s_waitcnt lgkmcnt(4)
	v_add_f32_e32 v24, v24, v25
	s_waitcnt lgkmcnt(3)
	v_add_f32_e32 v26, v26, v27
	v_cndmask_b32_e32 v19, v20, v21, vcc
	v_cndmask_b32_e64 v18, 0, 1, vcc
	v_cmp_gt_f32_e32 vcc, v22, v19
	s_waitcnt lgkmcnt(2)
	v_add_f32_e32 v28, v28, v29
	s_waitcnt lgkmcnt(1)
	v_add_f32_e32 v30, v30, v31
	v_cndmask_b32_e32 v19, v19, v22, vcc
	v_cndmask_b32_e64 v18, v18, 2, vcc
	v_cmp_gt_f32_e32 vcc, v24, v19
	s_waitcnt lgkmcnt(0)
	v_add_f32_e32 v32, v32, v33
	s_mov_b32 s18, 0xff7fc99e
	v_cndmask_b32_e32 v19, v19, v24, vcc
	v_cndmask_b32_e64 v18, v18, 3, vcc
	v_cmp_gt_f32_e32 vcc, v26, v19
	v_cmp_nlt_f32_e64 s[42:43], s18, v20
	s_nop 0
	v_cndmask_b32_e32 v19, v19, v26, vcc
	v_cndmask_b32_e64 v18, v18, 4, vcc
	v_cmp_gt_f32_e32 vcc, v28, v19
	s_nop 1
	v_cndmask_b32_e32 v19, v19, v28, vcc
	v_cndmask_b32_e64 v18, v18, 5, vcc
	v_cmp_ngt_f32_e32 vcc, v30, v19
	s_nop 1
	v_cndmask_b32_e32 v19, v30, v19, vcc
	v_cndmask_b32_e32 v18, 6, v18, vcc
	v_cmp_gt_f32_e64 s[4:5], v32, v19
	v_cmp_ngt_f32_e64 s[2:3], v32, v19
	s_nop 0
	v_cndmask_b32_e64 v18, v18, 7, s[4:5]
	v_cmp_eq_u32_e64 s[6:7], 0, v18
	s_or_b64 s[6:7], s[6:7], s[42:43]
	s_or_b64 s[4:5], vcc, s[4:5]
	v_cndmask_b32_e64 v20, v20, v205, s[6:7]
	v_cndmask_b32_e64 v23, 0, -1, s[6:7]
	v_cmp_ne_u32_e64 s[6:7], 1, v18
	v_cmp_gt_f32_e64 s[42:43], v21, v20
	s_and_b64 s[6:7], s[6:7], s[42:43]
	v_cndmask_b32_e64 v20, v20, v21, s[6:7]
	v_cndmask_b32_e64 v23, v23, 1, s[6:7]
	v_cmp_ne_u32_e64 s[6:7], 2, v18
	v_cmp_gt_f32_e64 s[42:43], v22, v20
	s_and_b64 s[6:7], s[6:7], s[42:43]
	v_cndmask_b32_e64 v20, v20, v22, s[6:7]
	v_cndmask_b32_e64 v21, v23, 2, s[6:7]
	v_cmp_ne_u32_e64 s[6:7], 3, v18
	v_cmp_gt_f32_e64 s[42:43], v24, v20
	s_and_b64 s[6:7], s[6:7], s[42:43]
	v_cndmask_b32_e64 v20, v20, v24, s[6:7]
	v_cndmask_b32_e64 v21, v21, 3, s[6:7]
	v_cmp_ne_u32_e64 s[6:7], 4, v18
	v_cmp_gt_f32_e64 s[42:43], v26, v20
	s_and_b64 s[6:7], s[6:7], s[42:43]
	v_cndmask_b32_e64 v20, v20, v26, s[6:7]
	v_cndmask_b32_e64 v21, v21, 4, s[6:7]
	v_cmp_ne_u32_e64 s[6:7], 5, v18
	v_cmp_gt_f32_e64 s[42:43], v28, v20
	s_and_b64 s[6:7], s[6:7], s[42:43]
	v_cndmask_b32_e64 v22, v20, v28, s[6:7]
	v_cmp_gt_f32_e32 vcc, v30, v22
	v_cndmask_b32_e64 v21, v21, 5, s[6:7]
	s_and_b64 vcc, s[4:5], vcc
	v_cndmask_b32_e64 v20, v21, 6, vcc
	v_cndmask_b32_e32 v21, v22, v30, vcc
	s_and_saveexec_b64 s[4:5], s[2:3]
	s_cbranch_execz .LBB0_1408
	v_cmp_gt_f32_e32 vcc, v32, v21
	s_and_saveexec_b64 s[2:3], vcc
	s_cbranch_execz .LBB0_1407
	v_mov_b32_e32 v20, 7
	v_mov_b32_e32 v21, v32
	s_branch .LBB0_1407
